# merge / w_out tiles: tile-start vmcnt(0) removed so the first LDS-DMA prologue no longer waits for the previous tile's epilogue stores (in-order vmcnt lets the first K-tile wait cover them)
# speedup vs baseline: 1.0057x; 1.0057x over previous
; DI void wait_vm0() { asm volatile("s_waitcnt vmcnt(0)" ::: "memory"); }
; DI int otid() { int t = threadIdx.x; asm volatile("" : "+v"(t)); return t; }
; template <int MB, bool SWAP>
; DI void gemm_kloop(f32x16 (&acc)[MB][2], const h16* __restrict__ A, int lda, const h16* __restrict__ B, int ldb, int K, char* lds) {
;     ...
;   const int tid = otid(), w = tid >> 6, lane = tid & 63;
;   const int wr = w >> 2, wc = w & 3;
;   const int lrow = w * 8 + (lane >> 3), pch = lane & 7;
;   const int gch = pch ^ ((lrow >> 1) & 7);
;   const unsigned voa = (unsigned)(lrow * lda + gch * 8) * 2u, vob = (unsigned)(lrow * ldb + gch * 8) * 2u;
;   const int lofs = lrow * 128 + pch * 16;
;   const int r32 = lane & 31, hh = lane >> 5, sw = (r32 >> 1) & 7;
;   const int a_rd = (wr * 32 * MB + r32) * 128;
;   const int b_rd = A_BYTES + (wc * 64 + r32) * 128;
;   const int nk = K >> 6;
;   constexpr int NP = MB + 4;
;   auto piece = [&](int p, int kt, int buf) {
;     char* s = lds + buf * STAGE;
;     if (p < MB) __builtin_amdgcn_global_load_lds((const unsigned*)((const char*)(A + (size_t)p * 64 * lda + kt * 64) + voa), (unsigned*)(s + p * 8192 + lofs), 16, 0, 0);
;     else __builtin_amdgcn_global_load_lds((const unsigned*)((const char*)(B + (size_t)(p - MB) * 64 * ldb + kt * 64) + vob), (unsigned*)(s + A_BYTES + (p - MB) * 8192 + lofs), 16, 0, 0);
;   };
;   wait_vm0();
; #pragma unroll
;   for (int p = 0; p < NP; ++p) piece(p, 0, 0);
; #pragma unroll
;   for (int p = 0; p < NP; ++p) piece(p, 1, 1);
; template <int MB>
; DI void merge_tile(const Params& P, int layer, size_t row0, int nt, char* smem) {
;     ...
;   for (int n = 0; n < 3; ++n) {
;     const h16* yn = (const h16*)(P.ws + (n == 0 ? WS_R2 : (n == 1 ? WS_YB : WS_YC)));
;     f32x16 pa2[MB][2];
;     half8 gpk[MB][2][2];
;     zero_acc<MB>(pa2);
;     gemm_kloop<MB, true>(pa2, hb + row0 * LDH, LDH, winT + (size_t)(G_OFF + n * 1024 + nt * 256) * LDH, LDH, D, smem);
.LBB0_39:
	v_mov_b32_e32 v5, v208
	s_lshl_b32 vcc_lo, s45, 10
	v_ashrrev_i32_e32 v11, 3, v5
	v_bfe_u32 v12, v5, 3, 3
	v_and_or_b32 v0, v11, -8, v12
	v_lshrrev_b32_e32 v1, 1, v0
	v_xor_b32_e32 v1, v1, v5
	v_lshlrev_b32_e32 v1, 3, v1
	v_mul_lo_u32 v2, v0, s6
	v_and_b32_e32 v13, 56, v1
	v_or_b32_e32 v1, v13, v2
	v_lshlrev_b32_e32 v128, 1, v1
	v_lshlrev_b32_e32 v1, 4, v5
	v_and_b32_e32 v1, 0x70, v1
	v_lshl_or_b32 v8, v0, 7, v1
	v_add_u32_e32 v10, 0, v8
	v_add_u32_e32 v15, 0x2000, v10
	v_readfirstlane_b32 s33, v10
	s_add_i32 s24, s74, vcc_lo
	s_nop 0
	v_lshl_add_u64 v[2:3], s[50:51], 0, v[128:129]
	s_mov_b32 m0, s33
	s_mov_b64 s[52:53], 0x22000
	v_readfirstlane_b32 s33, v15
	s_mul_i32 s84, s24, 0x440
	global_load_lds_dwordx4 v128, s[50:51]
	v_lshl_add_u64 v[6:7], v[2:3], 0, s[52:53]
	s_mov_b32 m0, s33
	s_lshl_b64 s[24:25], s[84:85], 1
	global_load_lds_dwordx4 v[6:7], off
	v_add_u32_e32 v6, 0x4000, v10
	s_add_u32 s24, s96, s24
	v_and_b32_e32 v0, 31, v5
	v_lshrrev_b32_e32 v1, 2, v5
	v_readfirstlane_b32 s33, v6
	s_addc_u32 s25, s97, s25
	v_and_or_b32 v14, v1, s7, v0
	v_lshlrev_b32_e32 v0, 7, v5
	s_mov_b32 m0, s33
	v_add_u32_e32 v15, 0x6000, v10
	v_and_b32_e32 v4, 0x6f80, v0
	v_lshl_add_u64 v[0:1], s[24:25], 0, v[128:129]
	global_load_lds_dwordx4 v128, s[24:25]
	v_readfirstlane_b32 s24, v15
	v_lshl_add_u64 v[6:7], v[0:1], 0, s[52:53]
	s_mov_b32 m0, s24
	s_mov_b64 s[24:25], 0x44000
	v_add_u32_e32 v15, 0x8000, v10
	global_load_lds_dwordx4 v[6:7], off
	v_lshl_add_u64 v[6:7], v[0:1], 0, s[24:25]
	v_readfirstlane_b32 s24, v15
	s_mov_b32 m0, s24
	s_mov_b64 s[24:25], 0x66000
	v_add_u32_e32 v15, 0xa000, v10
	global_load_lds_dwordx4 v[6:7], off
	v_lshl_add_u64 v[6:7], v[0:1], 0, s[24:25]
	v_readfirstlane_b32 s24, v15
	s_mov_b32 m0, s24
	v_lshl_add_u64 v[2:3], v[2:3], 0, s[22:23]
	global_load_lds_dwordx4 v[6:7], off
	v_add_u32_e32 v7, 0xc000, v10
	v_lshrrev_b32_e32 v9, 1, v5
	v_readfirstlane_b32 s24, v7
	s_mov_b32 m0, s24
	v_add_u32_e32 v7, s8, v8
	global_load_lds_dwordx4 v[2:3], off
	v_add_u32_e32 v2, 0xe000, v10
	v_bfe_u32 v15, v5, 5, 1
	v_readfirstlane_b32 s24, v2
	s_mov_b32 m0, s24
	v_readfirstlane_b32 s24, v7
	global_load_lds_dwordx4 v128, s[86:87]
	v_lshl_add_u64 v[2:3], v[0:1], 0, s[22:23]
	s_mov_b32 m0, s24
	s_mov_b64 s[24:25], 0x22080
	v_add_u32_e32 v7, s9, v8
	global_load_lds_dwordx4 v[2:3], off
	v_lshl_add_u64 v[2:3], v[0:1], 0, s[24:25]
	v_readfirstlane_b32 s24, v7
	s_mov_b32 m0, s24
	s_mov_b64 s[24:25], 0x44080
	v_add_u32_e32 v7, s79, v8
	global_load_lds_dwordx4 v[2:3], off
	v_lshl_add_u64 v[2:3], v[0:1], 0, s[24:25]
	v_readfirstlane_b32 s24, v7
	s_mov_b32 m0, s24
	s_mov_b64 s[24:25], 0x66080
	global_load_lds_dwordx4 v[2:3], off
	v_add_u32_e32 v2, s10, v8
	v_lshl_add_u64 v[0:1], v[0:1], 0, s[24:25]
	v_readfirstlane_b32 s24, v2
	s_mov_b32 m0, s24
	v_lshlrev_b32_e32 v6, 7, v14
	global_load_lds_dwordx4 v[0:1], off
	v_bfe_u32 v0, v5, 1, 3
	v_bitop3_b32 v1, v15, v9, 7 bitop3:0x78
	v_lshlrev_b32_e32 v9, 4, v1
	v_bitop3_b32 v1, v15, v0, 2 bitop3:0x36
	v_lshlrev_b32_e32 v8, 4, v1
	v_bitop3_b32 v1, v15, v0, 4 bitop3:0x36
	v_bitop3_b32 v0, v15, v0, 6 bitop3:0x36
	v_lshlrev_b32_e32 v5, 4, v0
	v_lshrrev_b32_e32 v0, 3, v11
	v_mul_lo_u32 v0, v0, s11
	v_mad_u32_u24 v0, v12, s6, v0
	v_or_b32_e32 v0, v0, v13
	v_lshlrev_b32_e32 v128, 1, v0
	v_lshlrev_b32_e32 v7, 4, v1
	v_lshl_add_u64 v[0:1], s[38:39], 0, v[128:129]
	v_lshl_add_u64 v[2:3], s[42:43], 0, v[128:129]
	s_mov_b64 s[80:81], 0
	s_mov_b32 s24, 0
	v_mov_b32_e32 v64, 0
	v_mov_b32_e32 v65, v197
	v_mov_b32_e32 v66, v197
	v_mov_b32_e32 v67, v197
	v_mov_b32_e32 v68, v197
	v_mov_b32_e32 v69, v197
	v_mov_b32_e32 v70, v197
	v_mov_b32_e32 v71, v197
	v_mov_b32_e32 v72, v197
	v_mov_b32_e32 v73, v197
	v_mov_b32_e32 v74, v197
	v_mov_b32_e32 v75, v197
	v_mov_b32_e32 v76, v197
	v_mov_b32_e32 v77, v197
	v_mov_b32_e32 v78, v197
	v_mov_b32_e32 v79, v197
	v_mov_b32_e32 v80, 0
	v_mov_b32_e32 v81, v197
	v_mov_b32_e32 v82, v197
	v_mov_b32_e32 v83, v197
	v_mov_b32_e32 v84, v197
	v_mov_b32_e32 v85, v197
	v_mov_b32_e32 v86, v197
	v_mov_b32_e32 v87, v197
	v_mov_b32_e32 v88, v197
	v_mov_b32_e32 v89, v197
	v_mov_b32_e32 v90, v197
	v_mov_b32_e32 v91, v197
	v_mov_b32_e32 v92, v197
	v_mov_b32_e32 v93, v197
	v_mov_b32_e32 v94, v197
	v_mov_b32_e32 v95, v197
	v_mov_b32_e32 v96, 0
	v_mov_b32_e32 v97, v197
	v_mov_b32_e32 v98, v197
	v_mov_b32_e32 v99, v197
	v_mov_b32_e32 v100, v197
	v_mov_b32_e32 v101, v197
	v_mov_b32_e32 v102, v197
	v_mov_b32_e32 v103, v197
	v_mov_b32_e32 v104, v197
	v_mov_b32_e32 v105, v197
	v_mov_b32_e32 v106, v197
	v_mov_b32_e32 v107, v197
	v_mov_b32_e32 v108, v197
	v_mov_b32_e32 v109, v197
	v_mov_b32_e32 v110, v197
	v_mov_b32_e32 v111, v197
	v_mov_b32_e32 v112, 0
	v_mov_b32_e32 v113, v197
	v_mov_b32_e32 v114, v197
	v_mov_b32_e32 v115, v197
	v_mov_b32_e32 v116, v197
	v_mov_b32_e32 v117, v197
	v_mov_b32_e32 v118, v197
	v_mov_b32_e32 v119, v197
	v_mov_b32_e32 v120, v197
	v_mov_b32_e32 v121, v197
	v_mov_b32_e32 v122, v197
	v_mov_b32_e32 v123, v197
	v_mov_b32_e32 v124, v197
	v_mov_b32_e32 v125, v197
	v_mov_b32_e32 v126, v197
	v_mov_b32_e32 v127, v197
	s_mov_b64 s[52:53], 0x3308100
	v_readfirstlane_b32 s25, v208
	s_nop 0
	s_lshr_b32 s25, s25, 8
	s_cmp_lg_u32 s25, 0
	s_cbranch_scc1 .Lstg40_top

; DI void wait_vm0() { asm volatile("s_waitcnt vmcnt(0)" ::: "memory"); }
; template <int MB, bool SWAP>
; DI void gemm_kloop(f32x16 (&acc)[MB][2], const h16* __restrict__ A, int lda, const h16* __restrict__ B, int ldb, int K, char* lds) {
;     ...
;   for (int kt = 0; kt < nk; ++kt) {
;     if (kt + 1 < nk) { if (MB == 2) asm volatile("s_waitcnt vmcnt(6)" ::: "memory"); else asm volatile("s_waitcnt vmcnt(5)" ::: "memory"); }
;     else wait_vm0();
;     __syncthreads();
;     const char* s = lds + cur * STAGE;
;     const int nbuf = cur == 0 ? 2 : cur - 1;
;     const bool more = kt + 2 < nk;
;     half8 af[2][MB], bf[2][2];
; #pragma unroll
;     for (int mb = 0; mb < MB; ++mb) af[0][mb] = *(const half8*)(s + a_rd + mb * 4096 + (((0 + hh) ^ sw) * 16));
; #pragma unroll
;     for (int nb = 0; nb < 2; ++nb) bf[0][nb] = *(const half8*)(s + b_rd + nb * 4096 + (((0 + hh) ^ sw) * 16));
; #pragma unroll
;     for (int ks = 0; ks < 4; ++ks) {
;       if (ks < 3) {
; #pragma unroll
;         for (int mb = 0; mb < MB; ++mb) af[(ks + 1) & 1][mb] = *(const half8*)(s + a_rd + mb * 4096 + (((2 * (ks + 1) + hh) ^ sw) * 16));
; #pragma unroll
;         for (int nb = 0; nb < 2; ++nb) bf[(ks + 1) & 1][nb] = *(const half8*)(s + b_rd + nb * 4096 + (((2 * (ks + 1) + hh) ^ sw) * 16));
;       }
;       if (more) {
;         if (2 * ks < NP) piece(2 * ks, kt + 2, nbuf);
;         if (2 * ks + 1 < NP) piece(2 * ks + 1, kt + 2, nbuf);
;       }
;       __builtin_amdgcn_sched_barrier(0);
;       __builtin_amdgcn_s_setprio(1);
; #pragma unroll
;       for (int mb = 0; mb < MB; ++mb)
; #pragma unroll
;         for (int nb = 0; nb < 2; ++nb)
;           acc[mb][nb] = SWAP ? __builtin_amdgcn_mfma_f32_32x32x16_f16(bf[ks & 1][nb], af[ks & 1][mb], acc[mb][nb], 0, 0, 0)
;                              : __builtin_amdgcn_mfma_f32_32x32x16_f16(af[ks & 1][mb], bf[ks & 1][nb], acc[mb][nb], 0, 0, 0);
;       __builtin_amdgcn_s_setprio(0);
;       __builtin_amdgcn_sched_barrier(0);
;     }
;     cur = cur == 2 ? 0 : cur + 1;
;   }
;   __syncthreads();
; template <int MB>
; DI void merge_tile(const Params& P, int layer, size_t row0, int nt, char* smem) {
;     ...
;     const h16* yn = (const h16*)(P.ws + (n == 0 ? WS_R2 : (n == 1 ? WS_YB : WS_YC)));
.Lstg40_join:
	s_cmp_eq_u32 s45, 1
	s_cselect_b32 s24, s12, 0x1ba66000
	s_cmp_lg_u32 s45, 0
	s_cselect_b32 s24, s24, 0x10f66000
	s_add_i32 s25, 0, 0x18000
	v_add_u32_e32 v38, s25, v6
	v_add_u32_e32 v10, v38, v9
	v_add3_u32 v18, s25, v9, v4
	v_add_u32_e32 v26, v38, v8
	v_add3_u32 v34, s25, v8, v4
	s_waitcnt vmcnt(6)
	s_waitcnt lgkmcnt(0)
	s_barrier
	ds_read_b128 v[0:3], v10
	ds_read_b128 v[10:13], v10 offset:4096
	ds_read_b128 v[14:17], v18 offset:16384
	ds_read_b128 v[18:21], v18 offset:20480
	ds_read_b128 v[22:25], v26
	ds_read_b128 v[26:29], v26 offset:4096
	ds_read_b128 v[30:33], v34 offset:16384
	ds_read_b128 v[34:37], v34 offset:20480
	s_mov_b32 vcc_hi, 0
	s_setprio 1
	s_waitcnt lgkmcnt(5)
	v_mfma_f32_32x32x16_f16 v[112:127], v[14:17], v[0:3], v[112:127]
	s_waitcnt lgkmcnt(4)
	v_mfma_f32_32x32x16_f16 v[96:111], v[18:21], v[0:3], v[96:111]
	v_mfma_f32_32x32x16_f16 v[80:95], v[14:17], v[10:13], v[80:95]
	v_mfma_f32_32x32x16_f16 v[64:79], v[18:21], v[10:13], v[64:79]
	s_setprio 0
	v_add_u32_e32 v10, v38, v7
	v_add3_u32 v18, s25, v7, v4
	ds_read_b128 v[0:3], v10
	ds_read_b128 v[10:13], v10 offset:4096
	ds_read_b128 v[14:17], v18 offset:16384
	ds_read_b128 v[18:21], v18 offset:20480
	s_setprio 1
	s_waitcnt lgkmcnt(5)
	v_mfma_f32_32x32x16_f16 v[112:127], v[30:33], v[22:25], v[112:127]
	s_waitcnt lgkmcnt(4)
	v_mfma_f32_32x32x16_f16 v[96:111], v[34:37], v[22:25], v[96:111]
	v_mfma_f32_32x32x16_f16 v[80:95], v[30:33], v[26:29], v[80:95]
	v_mfma_f32_32x32x16_f16 v[64:79], v[34:37], v[26:29], v[64:79]
	s_setprio 0
	v_add_u32_e32 v26, v38, v5
	v_add3_u32 v34, s25, v5, v4
	ds_read_b128 v[22:25], v26
	ds_read_b128 v[26:29], v26 offset:4096
	ds_read_b128 v[30:33], v34 offset:16384
	ds_read_b128 v[34:37], v34 offset:20480
	s_setprio 1
	s_waitcnt lgkmcnt(5)
	v_mfma_f32_32x32x16_f16 v[112:127], v[14:17], v[0:3], v[112:127]
	s_waitcnt lgkmcnt(4)
	v_mfma_f32_32x32x16_f16 v[96:111], v[18:21], v[0:3], v[96:111]
	v_mfma_f32_32x32x16_f16 v[80:95], v[14:17], v[10:13], v[80:95]
	v_mfma_f32_32x32x16_f16 v[64:79], v[18:21], v[10:13], v[64:79]
	s_setprio 0
	s_setprio 1
	s_waitcnt lgkmcnt(1)
	v_mfma_f32_32x32x16_f16 v[112:127], v[30:33], v[22:25], v[112:127]
	s_waitcnt lgkmcnt(0)
	v_mfma_f32_32x32x16_f16 v[96:111], v[34:37], v[22:25], v[96:111]
	v_mfma_f32_32x32x16_f16 v[80:95], v[30:33], v[26:29], v[80:95]
	v_mfma_f32_32x32x16_f16 v[64:79], v[34:37], v[26:29], v[64:79]
	s_setprio 0
	v_add_u32_e32 v6, 0, v6
	v_add_u32_e32 v4, 0, v4
	v_add_u32_e32 v10, v6, v9
	v_add_u32_e32 v9, v4, v9
	s_waitcnt vmcnt(0)
	s_barrier
	ds_read_b128 v[0:3], v10
	ds_read_b128 v[10:13], v10 offset:4096
	ds_read_b128 v[14:17], v9 offset:16384
	ds_read_b128 v[18:21], v9 offset:20480
	v_add_u32_e32 v9, v6, v8
	v_add_u32_e32 v8, v4, v8
	ds_read_b128 v[22:25], v9
	ds_read_b128 v[26:29], v9 offset:4096
	ds_read_b128 v[30:33], v8 offset:16384
	ds_read_b128 v[34:37], v8 offset:20480
	s_setprio 1
	s_waitcnt lgkmcnt(5)
	v_mfma_f32_32x32x16_f16 v[112:127], v[14:17], v[0:3], v[112:127]
	s_waitcnt lgkmcnt(4)
	v_mfma_f32_32x32x16_f16 v[96:111], v[18:21], v[0:3], v[96:111]
	v_mfma_f32_32x32x16_f16 v[80:95], v[14:17], v[10:13], v[80:95]
	v_mfma_f32_32x32x16_f16 v[64:79], v[18:21], v[10:13], v[64:79]
	s_setprio 0
	v_add_u32_e32 v8, v6, v7
	v_add_u32_e32 v7, v4, v7
	ds_read_b128 v[0:3], v8
	ds_read_b128 v[8:11], v8 offset:4096
	ds_read_b128 v[12:15], v7 offset:16384
	ds_read_b128 v[16:19], v7 offset:20480
	s_setprio 1
	s_waitcnt lgkmcnt(5)
	v_mfma_f32_32x32x16_f16 v[112:127], v[30:33], v[22:25], v[112:127]
	s_waitcnt lgkmcnt(4)
	v_mfma_f32_32x32x16_f16 v[96:111], v[34:37], v[22:25], v[96:111]
	v_mfma_f32_32x32x16_f16 v[80:95], v[30:33], v[26:29], v[80:95]
	v_mfma_f32_32x32x16_f16 v[64:79], v[34:37], v[26:29], v[64:79]
	s_setprio 0
	v_add_u32_e32 v6, v6, v5
	v_add_u32_e32 v28, v4, v5
	ds_read_b128 v[20:23], v6
	ds_read_b128 v[24:27], v6 offset:4096
	ds_read_b128 v[4:7], v28 offset:16384
	ds_read_b128 v[28:31], v28 offset:20480
	s_setprio 1
	s_waitcnt lgkmcnt(5)
	v_mfma_f32_32x32x16_f16 v[112:127], v[12:15], v[0:3], v[112:127]
	s_waitcnt lgkmcnt(4)
	v_mfma_f32_32x32x16_f16 v[96:111], v[16:19], v[0:3], v[96:111]
	v_mfma_f32_32x32x16_f16 v[80:95], v[12:15], v[8:11], v[80:95]
	v_mfma_f32_32x32x16_f16 v[64:79], v[16:19], v[8:11], v[64:79]
	s_setprio 0
	s_setprio 1
	s_waitcnt lgkmcnt(1)
	v_mfma_f32_32x32x16_f16 v[112:127], v[4:7], v[20:23], v[112:127]
	s_waitcnt lgkmcnt(0)
	v_mfma_f32_32x32x16_f16 v[96:111], v[28:31], v[20:23], v[96:111]
	v_mfma_f32_32x32x16_f16 v[80:95], v[4:7], v[24:27], v[80:95]
	v_mfma_f32_32x32x16_f16 v[64:79], v[28:31], v[24:27], v[64:79]
	s_setprio 0
	v_mov_b32_e32 v6, v208
	s_barrier
; DI void wait_vm0() { asm volatile("s_waitcnt vmcnt(0)" ::: "memory"); }
; DI int otid() { int t = threadIdx.x; asm volatile("" : "+v"(t)); return t; }
; template <int MB, bool SWAP>
; DI void gemm_kloop(f32x16 (&acc)[MB][2], const h16* __restrict__ A, int lda, const h16* __restrict__ B, int ldb, int K, char* lds) {
;     ...
;   const int tid = otid(), w = tid >> 6, lane = tid & 63;
;   const int wr = w >> 2, wc = w & 3;
;   const int lrow = w * 8 + (lane >> 3), pch = lane & 7;
;   const int gch = pch ^ ((lrow >> 1) & 7);
;   const unsigned voa = (unsigned)(lrow * lda + gch * 8) * 2u, vob = (unsigned)(lrow * ldb + gch * 8) * 2u;
;   const int lofs = lrow * 128 + pch * 16;
;   const int r32 = lane & 31, hh = lane >> 5, sw = (r32 >> 1) & 7;
;   const int a_rd = (wr * 32 * MB + r32) * 128;
;   const int b_rd = A_BYTES + (wc * 64 + r32) * 128;
;   const int nk = K >> 6;
;   constexpr int NP = MB + 4;
;   auto piece = [&](int p, int kt, int buf) {
;     char* s = lds + buf * STAGE;
;     if (p < MB) __builtin_amdgcn_global_load_lds((const unsigned*)((const char*)(A + (size_t)p * 64 * lda + kt * 64) + voa), (unsigned*)(s + p * 8192 + lofs), 16, 0, 0);
;     else __builtin_amdgcn_global_load_lds((const unsigned*)((const char*)(B + (size_t)(p - MB) * 64 * ldb + kt * 64) + vob), (unsigned*)(s + A_BYTES + (p - MB) * 8192 + lofs), 16, 0, 0);
;   };
;   wait_vm0();
; #pragma unroll
;   for (int p = 0; p < NP; ++p) piece(p, 0, 0);
; #pragma unroll
;   for (int p = 0; p < NP; ++p) piece(p, 1, 1);
; template <int MB>
; DI void merge_tile(const Params& P, int layer, size_t row0, int nt, char* smem) {
;     ...
;     zero_acc<MB>(pa2);
;     gemm_kloop<MB, true>(pa2, yn + row0 * LDY, LDY, wbrT + (size_t)(n * 1024 + nt * 256) * LDY, LDY, WB, smem);
	s_add_u32 s52, s3, s24
	v_ashrrev_i32_e32 v7, 3, v6
	v_bfe_u32 v8, v6, 3, 3
	v_and_or_b32 v0, v7, -8, v8
	v_lshrrev_b32_e32 v1, 1, v0
	v_xor_b32_e32 v1, v1, v6
	v_lshlrev_b32_e32 v1, 3, v1
	v_mul_lo_u32 v2, v0, s13
	v_and_b32_e32 v9, 56, v1
	v_or_b32_e32 v1, v9, v2
	v_lshlrev_b32_e32 v128, 1, v1
	v_lshlrev_b32_e32 v1, 4, v6
	v_and_b32_e32 v1, 0x70, v1
	v_lshl_or_b32 v10, v0, 7, v1
	s_addc_u32 s53, s2, 0
	s_or_b32 s25, vcc_lo, s71
	v_add_u32_e32 v205, 0, v10
	s_mul_i32 s84, s25, 0x240
	v_readfirstlane_b32 s25, v205
	s_nop 0
	s_mov_b32 m0, s25
	v_add_u32_e32 v13, 0x2000, v205
	v_lshl_add_u64 v[2:3], s[52:53], 0, v[128:129]
	global_load_lds_dwordx4 v128, s[52:53]
	s_mov_b64 s[52:53], 0x12000
	v_readfirstlane_b32 s25, v13
	s_lshl_b64 s[54:55], s[84:85], 1
	v_lshl_add_u64 v[4:5], v[2:3], 0, s[52:53]
	s_mov_b32 m0, s25
	s_add_u32 s54, s75, s54
	v_and_b32_e32 v0, 31, v6
	v_lshrrev_b32_e32 v1, 2, v6
	global_load_lds_dwordx4 v[4:5], off
	v_add_u32_e32 v4, 0x4000, v205
	s_addc_u32 s55, s76, s55
	v_and_or_b32 v12, v1, s7, v0
	v_lshlrev_b32_e32 v0, 7, v6
	v_readfirstlane_b32 s25, v4
	v_add_u32_e32 v13, 0x6000, v205
	v_and_b32_e32 v199, 0x6f80, v0
	v_lshl_add_u64 v[0:1], s[54:55], 0, v[128:129]
	s_mov_b32 m0, s25
	v_readfirstlane_b32 s25, v13
	v_add_u32_e32 v13, 0x8000, v205
	global_load_lds_dwordx4 v128, s[54:55]
	v_lshl_add_u64 v[4:5], v[0:1], 0, s[52:53]
	s_mov_b32 m0, s25
	s_mov_b64 s[52:53], 0x24000
	v_readfirstlane_b32 s25, v13
	v_add_u32_e32 v13, 0xa000, v205
	global_load_lds_dwordx4 v[4:5], off
	v_lshl_add_u64 v[4:5], v[0:1], 0, s[52:53]
	s_mov_b32 m0, s25
	s_mov_b64 s[52:53], 0x36000
	v_readfirstlane_b32 s25, v13
	v_lshlrev_b32_e32 v204, 7, v12
	v_add_u32_e32 v12, 0xc000, v205
	global_load_lds_dwordx4 v[4:5], off
	v_lshl_add_u64 v[4:5], v[0:1], 0, s[52:53]
	s_mov_b32 m0, s25
	v_readfirstlane_b32 s25, v12
	global_load_lds_dwordx4 v[4:5], off
	v_lshl_add_u64 v[4:5], v[2:3], 0, s[22:23]
	s_mov_b32 m0, s25
	s_mov_b64 s[52:53], 0x12080
	global_load_lds_dwordx4 v[4:5], off
	v_add_u32_e32 v4, 0xe000, v205
	v_lshl_add_u64 v[2:3], v[2:3], 0, s[52:53]
	v_readfirstlane_b32 s25, v4
	v_add_u32_e32 v4, s8, v10
	s_mov_b32 m0, s25
	v_readfirstlane_b32 s25, v4
	v_add_u32_e32 v4, s9, v10
	global_load_lds_dwordx4 v[2:3], off
	v_lshl_add_u64 v[2:3], v[0:1], 0, s[22:23]
	s_mov_b32 m0, s25
	v_readfirstlane_b32 s25, v4
	v_add_u32_e32 v4, s79, v10
	global_load_lds_dwordx4 v[2:3], off
	v_lshl_add_u64 v[2:3], v[0:1], 0, s[52:53]
	s_mov_b32 m0, s25
	s_mov_b64 s[52:53], 0x24080
	v_readfirstlane_b32 s25, v4
	global_load_lds_dwordx4 v[2:3], off
	v_lshl_add_u64 v[2:3], v[0:1], 0, s[52:53]
	s_mov_b32 m0, s25
	s_mov_b64 s[52:53], 0x36080
	global_load_lds_dwordx4 v[2:3], off
	v_add_u32_e32 v2, s10, v10
	v_lshl_add_u64 v[0:1], v[0:1], 0, s[52:53]
	v_readfirstlane_b32 s25, v2
	s_mov_b32 m0, s25
	v_lshrrev_b32_e32 v11, 1, v6
	global_load_lds_dwordx4 v[0:1], off
	v_bfe_u32 v13, v6, 5, 1
	v_bfe_u32 v0, v6, 1, 3
	v_bitop3_b32 v1, v13, v11, 7 bitop3:0x78
	v_lshlrev_b32_e32 v203, 4, v1
	v_bitop3_b32 v1, v13, v0, 2 bitop3:0x36
	v_lshlrev_b32_e32 v202, 4, v1
	v_bitop3_b32 v1, v13, v0, 4 bitop3:0x36
	v_bitop3_b32 v0, v13, v0, 6 bitop3:0x36
	v_lshlrev_b32_e32 v200, 4, v0
	v_lshrrev_b32_e32 v0, 3, v7
	v_mul_lo_u32 v0, v0, s14
	v_mad_u32_u24 v0, v8, s13, v0
	v_or_b32_e32 v0, v0, v9
	s_add_u32 s24, s70, s24
	v_lshlrev_b32_e32 v128, 1, v0
	s_addc_u32 s25, s44, 0
	v_mov_b32_e32 v0, 0
	v_lshlrev_b32_e32 v201, 4, v1
	v_lshl_add_u64 v[186:187], s[24:25], 0, v[128:129]
	v_lshl_add_u64 v[188:189], s[40:41], 0, v[128:129]
	s_mov_b64 s[80:81], 0
	v_mov_b32_e32 v1, v0
	v_mov_b32_e32 v2, v0
	v_mov_b32_e32 v3, v0
	v_mov_b32_e32 v4, v0
	v_mov_b32_e32 v5, v0
	v_mov_b32_e32 v6, v0
	v_mov_b32_e32 v7, v0
	v_mov_b32_e32 v8, v0
	v_mov_b32_e32 v9, v0
	v_mov_b32_e32 v10, v0
	v_mov_b32_e32 v11, v0
	v_mov_b32_e32 v12, v0
	v_mov_b32_e32 v13, v0
	v_mov_b32_e32 v14, v0
	v_mov_b32_e32 v15, v0
	v_mov_b32_e32 v16, v0
	v_mov_b32_e32 v17, v0
	v_mov_b32_e32 v18, v0
	v_mov_b32_e32 v19, v0
	v_mov_b32_e32 v20, v0
	v_mov_b32_e32 v21, v0
	v_mov_b32_e32 v22, v0
	v_mov_b32_e32 v23, v0
	v_mov_b32_e32 v24, v0
	v_mov_b32_e32 v25, v0
	v_mov_b32_e32 v26, v0
	v_mov_b32_e32 v27, v0
	v_mov_b32_e32 v28, v0
	v_mov_b32_e32 v29, v0
	v_mov_b32_e32 v30, v0
	v_mov_b32_e32 v31, v0
	v_mov_b32_e32 v32, v0
	v_mov_b32_e32 v33, v0
	v_mov_b32_e32 v34, v0
	v_mov_b32_e32 v35, v0
	v_mov_b32_e32 v36, v0
	v_mov_b32_e32 v37, v0
	v_mov_b32_e32 v38, v0
	v_mov_b32_e32 v39, v0
	v_mov_b32_e32 v40, v0
	v_mov_b32_e32 v41, v0
	v_mov_b32_e32 v42, v0
	v_mov_b32_e32 v43, v0
	v_mov_b32_e32 v44, v0
	v_mov_b32_e32 v45, v0
	v_mov_b32_e32 v46, v0
	v_mov_b32_e32 v47, v0
	v_mov_b32_e32 v48, v0
	v_mov_b32_e32 v49, v0
	v_mov_b32_e32 v50, v0
	v_mov_b32_e32 v51, v0
	v_mov_b32_e32 v52, v0
	v_mov_b32_e32 v53, v0
	v_mov_b32_e32 v54, v0
	v_mov_b32_e32 v55, v0
	v_mov_b32_e32 v56, v0
	v_mov_b32_e32 v57, v0
	v_mov_b32_e32 v58, v0
	v_mov_b32_e32 v59, v0
	v_mov_b32_e32 v60, v0
	v_mov_b32_e32 v61, v0
	v_mov_b32_e32 v62, v0
	v_mov_b32_e32 v63, v0
	s_mov_b64 s[52:53], 0x1188100
	v_readfirstlane_b32 s25, v208
	s_nop 0
	s_lshr_b32 s25, s25, 8
	s_cmp_lg_u32 s25, 0
	s_cbranch_scc1 .Lstg42_top

; DI void wait_vm0() { asm volatile("s_waitcnt vmcnt(0)" ::: "memory"); }
; DI int otid() { int t = threadIdx.x; asm volatile("" : "+v"(t)); return t; }
; template <int MB, bool SWAP>
; DI void gemm_kloop(f32x16 (&acc)[MB][2], const h16* __restrict__ A, int lda, const h16* __restrict__ B, int ldb, int K, char* lds) {
;     ...
;   const int tid = otid(), w = tid >> 6, lane = tid & 63;
;   const int wr = w >> 2, wc = w & 3;
;   const int lrow = w * 8 + (lane >> 3), pch = lane & 7;
;   const int gch = pch ^ ((lrow >> 1) & 7);
;   const unsigned voa = (unsigned)(lrow * lda + gch * 8) * 2u, vob = (unsigned)(lrow * ldb + gch * 8) * 2u;
;   const int lofs = lrow * 128 + pch * 16;
;   const int r32 = lane & 31, hh = lane >> 5, sw = (r32 >> 1) & 7;
;   const int a_rd = (wr * 32 * MB + r32) * 128;
;   const int b_rd = A_BYTES + (wc * 64 + r32) * 128;
;   const int nk = K >> 6;
;   constexpr int NP = MB + 4;
;   auto piece = [&](int p, int kt, int buf) {
;     char* s = lds + buf * STAGE;
;     if (p < MB) __builtin_amdgcn_global_load_lds((const unsigned*)((const char*)(A + (size_t)p * 64 * lda + kt * 64) + voa), (unsigned*)(s + p * 8192 + lofs), 16, 0, 0);
;     else __builtin_amdgcn_global_load_lds((const unsigned*)((const char*)(B + (size_t)(p - MB) * 64 * ldb + kt * 64) + vob), (unsigned*)(s + A_BYTES + (p - MB) * 8192 + lofs), 16, 0, 0);
;   };
;   wait_vm0();
; #pragma unroll
;   for (int p = 0; p < NP; ++p) piece(p, 0, 0);
; #pragma unroll
;   for (int p = 0; p < NP; ++p) piece(p, 1, 1);
;   int cur = 0;
;   for (int kt = 0; kt < nk; ++kt) {
;     if (kt + 1 < nk) { if (MB == 2) asm volatile("s_waitcnt vmcnt(6)" ::: "memory"); else asm volatile("s_waitcnt vmcnt(5)" ::: "memory"); }
;     else wait_vm0();
;     __syncthreads();
; template <int MB>
; DI void merge_tile(const Params& P, int layer, size_t row0, int nt, char* smem) {
;     ...
;   for (int n = 0; n < 3; ++n) {
;     const h16* yn = (const h16*)(P.ws + (n == 0 ? WS_R2 : (n == 1 ? WS_YB : WS_YC)));
;     f32x16 pa2[MB][2];
;     half8 gpk[MB][2][2];
;     zero_acc<MB>(pa2);
;     gemm_kloop<MB, true>(pa2, hb + row0 * LDH, LDH, winT + (size_t)(G_OFF + n * 1024 + nt * 256) * LDH, LDH, D, smem);
.LBB0_62:
	v_mov_b32_e32 v6, v208
	s_lshl_b32 s51, s97, 10
	v_ashrrev_i32_e32 v7, 3, v6
	v_bfe_u32 v8, v6, 3, 3
	v_and_or_b32 v0, v7, -8, v8
	v_lshrrev_b32_e32 v1, 1, v0
	v_xor_b32_e32 v1, v1, v6
	v_lshlrev_b32_e32 v1, 3, v1
	v_mul_lo_u32 v2, v0, s6
	v_and_b32_e32 v9, 56, v1
	v_or_b32_e32 v1, v9, v2
	v_lshlrev_b32_e32 v128, 1, v1
	v_lshlrev_b32_e32 v1, 4, v6
	v_and_b32_e32 v1, 0x70, v1
	s_add_i32 s0, s86, s51
	v_lshl_or_b32 v10, v0, 7, v1
	s_mul_i32 s84, s0, 0x440
	v_add_u32_e32 v42, 0, v10
	s_lshl_b64 s[0:1], s[84:85], 1
	v_readfirstlane_b32 s2, v42
	v_add_u32_e32 v4, 0x2000, v42
	s_add_u32 s0, s70, s0
	s_nop 0
	s_mov_b32 m0, s2
	v_readfirstlane_b32 s2, v4
	s_addc_u32 s1, s71, s1
	global_load_lds_dwordx4 v128, s[38:39]
	s_mov_b32 m0, s2
	v_lshl_add_u64 v[0:1], s[0:1], 0, v[128:129]
	global_load_lds_dwordx4 v128, s[0:1]
	s_mov_b64 s[0:1], 0x22000
	v_add_u32_e32 v11, 0x4000, v42
	v_lshl_add_u64 v[4:5], v[0:1], 0, s[0:1]
	v_readfirstlane_b32 s0, v11
	s_mov_b32 m0, s0
	s_mov_b64 s[0:1], 0x44000
	v_add_u32_e32 v11, 0x6000, v42
	global_load_lds_dwordx4 v[4:5], off
	v_lshl_add_u64 v[4:5], v[0:1], 0, s[0:1]
	v_readfirstlane_b32 s0, v11
	s_mov_b32 m0, s0
	s_mov_b64 s[0:1], 0x66000
	v_add_u32_e32 v11, 0x8000, v42
	global_load_lds_dwordx4 v[4:5], off
	v_lshl_add_u64 v[4:5], v[0:1], 0, s[0:1]
	v_readfirstlane_b32 s0, v11
	s_mov_b32 m0, s0
	v_lshl_add_u64 v[2:3], s[38:39], 0, v[128:129]
	global_load_lds_dwordx4 v[4:5], off
	v_add_u32_e32 v4, 0xa000, v42
	v_lshl_add_u64 v[2:3], v[2:3], 0, s[22:23]
	v_readfirstlane_b32 s0, v4
	v_add_u32_e32 v4, 0xc000, v42
	s_mov_b32 m0, s0
	v_readfirstlane_b32 s0, v4
	global_load_lds_dwordx4 v[2:3], off
	v_lshl_add_u64 v[2:3], v[0:1], 0, s[22:23]
	s_mov_b32 m0, s0
	s_mov_b64 s[0:1], 0x22080
	v_add_u32_e32 v4, 0xe000, v42
	global_load_lds_dwordx4 v[2:3], off
	v_lshl_add_u64 v[2:3], v[0:1], 0, s[0:1]
	v_readfirstlane_b32 s0, v4
	s_mov_b32 m0, s0
	s_mov_b64 s[0:1], 0x44080
	v_add_u32_e32 v4, s8, v10
	global_load_lds_dwordx4 v[2:3], off
	v_lshl_add_u64 v[2:3], v[0:1], 0, s[0:1]
	v_readfirstlane_b32 s0, v4
	s_mov_b32 m0, s0
	s_mov_b64 s[0:1], 0x66080
	global_load_lds_dwordx4 v[2:3], off
	v_add_u32_e32 v2, s9, v10
	v_lshl_add_u64 v[0:1], v[0:1], 0, s[0:1]
	v_readfirstlane_b32 s0, v2
	s_mov_b32 m0, s0
	v_lshlrev_b32_e32 v2, 7, v6
	global_load_lds_dwordx4 v[0:1], off
	v_and_b32_e32 v0, 31, v6
	v_lshrrev_b32_e32 v1, 1, v6
	v_and_or_b32 v0, v7, s16, v0
	v_and_b32_e32 v39, 0x6f80, v2
	v_bfe_u32 v2, v6, 5, 1
	v_lshlrev_b32_e32 v41, 7, v0
	v_bfe_u32 v0, v6, 1, 3
	v_bitop3_b32 v1, v2, v1, 7 bitop3:0x78
	v_lshlrev_b32_e32 v40, 4, v1
	v_bitop3_b32 v1, v2, v0, 2 bitop3:0x36
	v_lshlrev_b32_e32 v38, 4, v1
	v_bitop3_b32 v1, v2, v0, 4 bitop3:0x36
	v_bitop3_b32 v0, v2, v0, 6 bitop3:0x36
	v_lshlrev_b32_e32 v36, 4, v0
	v_lshrrev_b32_e32 v0, 3, v7
	v_mul_lo_u32 v0, v0, s11
	v_mad_u32_u24 v0, v8, s6, v0
	v_or_b32_e32 v0, v0, v9
	v_lshlrev_b32_e32 v128, 1, v0
	v_lshlrev_b32_e32 v37, 4, v1
	v_lshl_add_u64 v[32:33], s[40:41], 0, v[128:129]
	v_lshl_add_u64 v[34:35], s[42:43], 0, v[128:129]
	s_mov_b64 s[2:3], 0
	s_mov_b32 s0, 0
	v_mov_b32_e32 v16, 0
	v_mov_b32_e32 v17, v108
	v_mov_b32_e32 v18, v108
	v_mov_b32_e32 v19, v108
	v_mov_b32_e32 v20, v108
	v_mov_b32_e32 v21, v108
	v_mov_b32_e32 v22, v108
	v_mov_b32_e32 v23, v108
	v_mov_b32_e32 v24, v108
	v_mov_b32_e32 v25, v108
	v_mov_b32_e32 v26, v108
	v_mov_b32_e32 v27, v108
	v_mov_b32_e32 v28, v108
	v_mov_b32_e32 v29, v108
	v_mov_b32_e32 v30, v108
	v_mov_b32_e32 v31, v108
	v_mov_b32_e32 v0, 0
	v_mov_b32_e32 v1, v108
	v_mov_b32_e32 v2, v108
	v_mov_b32_e32 v3, v108
	v_mov_b32_e32 v4, v108
	v_mov_b32_e32 v5, v108
	v_mov_b32_e32 v6, v108
	v_mov_b32_e32 v7, v108
	v_mov_b32_e32 v8, v108
	v_mov_b32_e32 v9, v108
	v_mov_b32_e32 v10, v108
	v_mov_b32_e32 v11, v108
	v_mov_b32_e32 v12, v108
	v_mov_b32_e32 v13, v108
	v_mov_b32_e32 v14, v108
	v_mov_b32_e32 v15, v108
	s_mov_b64 s[52:53], 0xb6c180
	s_mov_b64 s[54:55], 0xb4a180
.LBB0_63:
	s_mul_i32 s1, s0, 0xa000
	s_add_i32 s24, s1, 0
	s_add_i32 s1, s1, 0xffff6000
	s_cmp_lg_u32 s0, 0
	s_cselect_b32 s1, s1, 0x14000
	v_add_u32_e32 v110, s1, v42
	v_add_u32_e32 v43, s24, v41
	v_add_u32_e32 v109, s24, v39
	v_add_u32_e32 v111, 0x2000, v110
	v_lshl_add_u64 v[100:101], v[32:33], 0, s[2:3]
	v_readfirstlane_b32 s1, v110
	v_add_u32_e32 v76, v109, v40
	v_lshl_add_u64 v[96:97], v[34:35], 0, s[2:3]
	v_add_u32_e32 v80, v43, v40
	v_add_u32_e32 v84, v43, v38
	v_add_u32_e32 v92, v109, v38
	v_lshl_add_u64 v[102:103], v[100:101], 0, s[90:91]
	s_mov_b32 m0, s1
	v_readfirstlane_b32 s1, v111
	s_waitcnt vmcnt(5)
	s_waitcnt lgkmcnt(0)
	s_barrier
; DI void wait_vm0() { asm volatile("s_waitcnt vmcnt(0)" ::: "memory"); }
; template <int MB, bool SWAP>
; DI void gemm_kloop(f32x16 (&acc)[MB][2], const h16* __restrict__ A, int lda, const h16* __restrict__ B, int ldb, int K, char* lds) {
;     ...
;   for (int kt = 0; kt < nk; ++kt) {
;     if (kt + 1 < nk) { if (MB == 2) asm volatile("s_waitcnt vmcnt(6)" ::: "memory"); else asm volatile("s_waitcnt vmcnt(5)" ::: "memory"); }
;     else wait_vm0();
;     __syncthreads();
;     const char* s = lds + cur * STAGE;
;     const int nbuf = cur == 0 ? 2 : cur - 1;
;     const bool more = kt + 2 < nk;
;     half8 af[2][MB], bf[2][2];
; #pragma unroll
;     for (int mb = 0; mb < MB; ++mb) af[0][mb] = *(const half8*)(s + a_rd + mb * 4096 + (((0 + hh) ^ sw) * 16));
; #pragma unroll
;     for (int nb = 0; nb < 2; ++nb) bf[0][nb] = *(const half8*)(s + b_rd + nb * 4096 + (((0 + hh) ^ sw) * 16));
; #pragma unroll
;     for (int ks = 0; ks < 4; ++ks) {
;       if (ks < 3) {
; #pragma unroll
;         for (int mb = 0; mb < MB; ++mb) af[(ks + 1) & 1][mb] = *(const half8*)(s + a_rd + mb * 4096 + (((2 * (ks + 1) + hh) ^ sw) * 16));
; #pragma unroll
;         for (int nb = 0; nb < 2; ++nb) bf[(ks + 1) & 1][nb] = *(const half8*)(s + b_rd + nb * 4096 + (((2 * (ks + 1) + hh) ^ sw) * 16));
;       }
;       if (more) {
;         if (2 * ks < NP) piece(2 * ks, kt + 2, nbuf);
;         if (2 * ks + 1 < NP) piece(2 * ks + 1, kt + 2, nbuf);
;       }
;       __builtin_amdgcn_sched_barrier(0);
;       __builtin_amdgcn_s_setprio(1);
; #pragma unroll
;       for (int mb = 0; mb < MB; ++mb)
; #pragma unroll
;         for (int nb = 0; nb < 2; ++nb)
;           acc[mb][nb] = SWAP ? __builtin_amdgcn_mfma_f32_32x32x16_f16(bf[ks & 1][nb], af[ks & 1][mb], acc[mb][nb], 0, 0, 0)
;                              : __builtin_amdgcn_mfma_f32_32x32x16_f16(af[ks & 1][mb], bf[ks & 1][nb], acc[mb][nb], 0, 0, 0);
;       __builtin_amdgcn_s_setprio(0);
;       __builtin_amdgcn_sched_barrier(0);
;     }
;     cur = cur == 2 ? 0 : cur + 1;
;   }
;   __syncthreads();
	ds_read_b128 v[72:75], v76 offset:8192
	ds_read_b128 v[76:79], v76 offset:12288
	v_lshl_add_u64 v[98:99], v[96:97], 0, s[72:73]
	ds_read_b128 v[80:83], v80
	ds_read_b128 v[84:87], v84
	ds_read_b128 v[88:91], v92 offset:8192
	ds_read_b128 v[92:95], v92 offset:12288
	global_load_lds_dwordx4 v[102:103], off
	s_mov_b32 m0, s1
	s_nop 0
	global_load_lds_dwordx4 v[98:99], off
	s_setprio 1
	s_waitcnt lgkmcnt(0)
	v_mfma_f32_32x32x16_f16 v[16:31], v[72:75], v[80:83], v[16:31]
	v_mfma_f32_32x32x16_f16 v[0:15], v[76:79], v[80:83], v[0:15]
	s_setprio 0
	v_add_u32_e32 v112, 0x4000, v110
	v_add_u32_e32 v111, 0x6000, v110
	v_readfirstlane_b32 s1, v112
	v_add_u32_e32 v72, v43, v37
	v_add_u32_e32 v80, v109, v37
	v_lshl_add_u64 v[102:103], v[96:97], 0, s[88:89]
	s_mov_b32 m0, s1
	v_readfirstlane_b32 s1, v111
	ds_read_b128 v[72:75], v72
	ds_read_b128 v[76:79], v80 offset:8192
	ds_read_b128 v[80:83], v80 offset:12288
	v_lshl_add_u64 v[98:99], v[96:97], 0, s[68:69]
	global_load_lds_dwordx4 v[102:103], off
	s_mov_b32 m0, s1
	s_nop 0
	global_load_lds_dwordx4 v[98:99], off
	s_setprio 1
	v_mfma_f32_32x32x16_f16 v[16:31], v[88:91], v[84:87], v[16:31]
	v_mfma_f32_32x32x16_f16 v[0:15], v[92:95], v[84:87], v[0:15]
	s_setprio 0
	v_add_u32_e32 v43, v43, v36
	v_add_u32_e32 v92, v109, v36
	ds_read_b128 v[84:87], v43
	ds_read_b128 v[88:91], v92 offset:8192
	ds_read_b128 v[92:95], v92 offset:12288
	v_add_u32_e32 v43, 0x8000, v110
	v_lshl_add_u64 v[98:99], v[96:97], 0, s[34:35]
	v_readfirstlane_b32 s1, v43
	s_mov_b32 m0, s1
	s_nop 0
	global_load_lds_dwordx4 v[98:99], off
	s_setprio 1
	s_waitcnt lgkmcnt(0)
	v_mfma_f32_32x32x16_f16 v[16:31], v[76:79], v[72:75], v[16:31]
	v_mfma_f32_32x32x16_f16 v[0:15], v[80:83], v[72:75], v[0:15]
	s_setprio 0
	s_setprio 1
	v_mfma_f32_32x32x16_f16 v[16:31], v[88:91], v[84:87], v[16:31]
	v_mfma_f32_32x32x16_f16 v[0:15], v[92:95], v[84:87], v[0:15]
	s_setprio 0
	s_add_i32 s1, s0, 1
	s_cmp_lg_u32 s0, 2
	s_cselect_b32 s0, s1, 0
	s_mul_i32 s1, s0, 0xa000
	s_add_i32 s24, s1, 0
	s_add_i32 s1, s1, 0xffff6000
	s_cmp_lg_u32 s0, 0
	s_cselect_b32 s1, s1, 0x14000
	v_add_u32_e32 v103, s1, v42
	v_add_u32_e32 v43, s24, v41
	v_add_u32_e32 v102, s24, v39
	v_add_u32_e32 v109, 0x2000, v103
	v_readfirstlane_b32 s1, v103
	v_add_u32_e32 v76, v102, v40
	v_add_u32_e32 v80, v43, v40
	v_add_u32_e32 v84, v43, v38
	v_add_u32_e32 v92, v102, v38
	v_lshl_add_u64 v[100:101], v[100:101], 0, vcc
	s_mov_b32 m0, s1
	v_readfirstlane_b32 s1, v109
	s_waitcnt vmcnt(5)
	s_waitcnt lgkmcnt(0)
	s_barrier
	ds_read_b128 v[72:75], v76 offset:8192
	ds_read_b128 v[76:79], v76 offset:12288
	v_lshl_add_u64 v[98:99], v[96:97], 0, s[44:45]
	ds_read_b128 v[80:83], v80
	ds_read_b128 v[84:87], v84
	ds_read_b128 v[88:91], v92 offset:8192
	ds_read_b128 v[92:95], v92 offset:12288
	global_load_lds_dwordx4 v[100:101], off
	s_mov_b32 m0, s1
	s_nop 0
	global_load_lds_dwordx4 v[98:99], off
	s_setprio 1
	s_waitcnt lgkmcnt(0)
	v_mfma_f32_32x32x16_f16 v[16:31], v[72:75], v[80:83], v[16:31]
	v_mfma_f32_32x32x16_f16 v[0:15], v[76:79], v[80:83], v[0:15]
	s_setprio 0
	v_add_u32_e32 v110, 0x4000, v103
	v_add_u32_e32 v109, 0x6000, v103
	v_readfirstlane_b32 s1, v110
	v_add_u32_e32 v72, v43, v37
	v_add_u32_e32 v80, v102, v37
	v_lshl_add_u64 v[100:101], v[96:97], 0, s[54:55]
	s_mov_b32 m0, s1
	v_readfirstlane_b32 s1, v109
	ds_read_b128 v[72:75], v72
	ds_read_b128 v[76:79], v80 offset:8192
	ds_read_b128 v[80:83], v80 offset:12288
	v_lshl_add_u64 v[98:99], v[96:97], 0, s[52:53]
	global_load_lds_dwordx4 v[100:101], off
	s_mov_b32 m0, s1
	s_nop 0
	global_load_lds_dwordx4 v[98:99], off
	s_setprio 1
	v_mfma_f32_32x32x16_f16 v[16:31], v[88:91], v[84:87], v[16:31]
	v_mfma_f32_32x32x16_f16 v[0:15], v[92:95], v[84:87], v[0:15]
	s_setprio 0
	v_add_u32_e32 v43, v43, v36
	v_add_u32_e32 v92, v102, v36
	ds_read_b128 v[84:87], v43
	ds_read_b128 v[88:91], v92 offset:8192
	ds_read_b128 v[92:95], v92 offset:12288
	v_add_u32_e32 v43, 0x8000, v103
	v_lshl_add_u64 v[96:97], v[96:97], 0, s[94:95]
	v_readfirstlane_b32 s1, v43
	s_mov_b32 m0, s1
	s_nop 0
	global_load_lds_dwordx4 v[96:97], off
	s_setprio 1
	s_waitcnt lgkmcnt(0)
	v_mfma_f32_32x32x16_f16 v[16:31], v[76:79], v[72:75], v[16:31]
	v_mfma_f32_32x32x16_f16 v[0:15], v[80:83], v[72:75], v[0:15]
	s_setprio 0
	s_setprio 1
	v_mfma_f32_32x32x16_f16 v[16:31], v[88:91], v[84:87], v[16:31]
	v_mfma_f32_32x32x16_f16 v[0:15], v[92:95], v[84:87], v[0:15]
	s_setprio 0
	s_add_i32 s1, s0, 1
	s_cmp_lg_u32 s0, 2
	s_cselect_b32 s0, s1, 0
	s_add_u32 s2, s2, 0x100
	s_addc_u32 s3, s3, 0
	s_cmpk_eq_i32 s2, 0x700
	s_cbranch_scc0 .LBB0_63
	v_add_u32_e32 v42, s79, v41
	v_add3_u32 v43, s79, v40, v39
	s_waitcnt vmcnt(5)
	s_waitcnt lgkmcnt(0)
	s_barrier
	ds_read_b128 v[32:35], v43 offset:8192
	ds_read_b128 v[72:75], v43 offset:12288
	v_add_u32_e32 v43, v42, v40
	v_add_u32_e32 v80, v42, v38
	ds_read_b128 v[76:79], v43
	ds_read_b128 v[80:83], v80
	v_add3_u32 v43, s79, v38, v39
	ds_read_b128 v[84:87], v43 offset:8192
	ds_read_b128 v[88:91], v43 offset:12288
	s_cmp_eq_u32 s97, 1
	s_cselect_b32 s0, s12, 0x1ba66000
	s_cmp_lg_u32 s97, 0
	s_cselect_b32 s0, s0, 0x10f66000
	s_setprio 1
	s_waitcnt lgkmcnt(3)
	v_mfma_f32_32x32x16_f16 v[16:31], v[32:35], v[76:79], v[16:31]
	v_mfma_f32_32x32x16_f16 v[0:15], v[72:75], v[76:79], v[0:15]
	s_setprio 0
	v_add_u32_e32 v32, v42, v37
	v_add3_u32 v43, s79, v37, v39
	ds_read_b128 v[32:35], v32
	ds_read_b128 v[72:75], v43 offset:8192
	ds_read_b128 v[76:79], v43 offset:12288
	s_setprio 1
	s_waitcnt lgkmcnt(4)
	v_mfma_f32_32x32x16_f16 v[16:31], v[84:87], v[80:83], v[16:31]
	s_waitcnt lgkmcnt(3)
	v_mfma_f32_32x32x16_f16 v[0:15], v[88:91], v[80:83], v[0:15]
	s_setprio 0
	v_add_u32_e32 v42, v42, v36
	v_add3_u32 v43, s79, v36, v39
	ds_read_b128 v[80:83], v42
	ds_read_b128 v[84:87], v43 offset:8192
	ds_read_b128 v[88:91], v43 offset:12288
	s_setprio 1
	s_waitcnt lgkmcnt(4)
	v_mfma_f32_32x32x16_f16 v[16:31], v[72:75], v[32:35], v[16:31]
	s_waitcnt lgkmcnt(3)
	v_mfma_f32_32x32x16_f16 v[0:15], v[76:79], v[32:35], v[0:15]
	s_setprio 0
	s_setprio 1
	s_waitcnt lgkmcnt(1)
	v_mfma_f32_32x32x16_f16 v[16:31], v[84:87], v[80:83], v[16:31]
	s_waitcnt lgkmcnt(0)
	v_mfma_f32_32x32x16_f16 v[0:15], v[88:91], v[80:83], v[0:15]
	s_setprio 0
	v_add_u32_e32 v89, 0, v39
	v_add_u32_e32 v88, 0, v41
	v_add_u32_e32 v39, v89, v40
	s_waitcnt vmcnt(0)
	s_barrier
; DI float sigmoid_f(float x) { return 1.f / (1.f + __expf(-x)); }
; template <int MB, bool SWAP>
; DI void gemm_kloop(f32x16 (&acc)[MB][2], const h16* __restrict__ A, int lda, const h16* __restrict__ B, int ldb, int K, char* lds) {
;     ...
;   for (int kt = 0; kt < nk; ++kt) {
;     if (kt + 1 < nk) { if (MB == 2) asm volatile("s_waitcnt vmcnt(6)" ::: "memory"); else asm volatile("s_waitcnt vmcnt(5)" ::: "memory"); }
;     else wait_vm0();
;     __syncthreads();
;     const char* s = lds + cur * STAGE;
;     const int nbuf = cur == 0 ? 2 : cur - 1;
;     const bool more = kt + 2 < nk;
;     half8 af[2][MB], bf[2][2];
; #pragma unroll
;     for (int mb = 0; mb < MB; ++mb) af[0][mb] = *(const half8*)(s + a_rd + mb * 4096 + (((0 + hh) ^ sw) * 16));
; #pragma unroll
;     for (int nb = 0; nb < 2; ++nb) bf[0][nb] = *(const half8*)(s + b_rd + nb * 4096 + (((0 + hh) ^ sw) * 16));
; #pragma unroll
;     for (int ks = 0; ks < 4; ++ks) {
;       if (ks < 3) {
; #pragma unroll
;         for (int mb = 0; mb < MB; ++mb) af[(ks + 1) & 1][mb] = *(const half8*)(s + a_rd + mb * 4096 + (((2 * (ks + 1) + hh) ^ sw) * 16));
; #pragma unroll
;         for (int nb = 0; nb < 2; ++nb) bf[(ks + 1) & 1][nb] = *(const half8*)(s + b_rd + nb * 4096 + (((2 * (ks + 1) + hh) ^ sw) * 16));
;       }
;       if (more) {
;         if (2 * ks < NP) piece(2 * ks, kt + 2, nbuf);
;         if (2 * ks + 1 < NP) piece(2 * ks + 1, kt + 2, nbuf);
;       }
;       __builtin_amdgcn_sched_barrier(0);
;       __builtin_amdgcn_s_setprio(1);
; #pragma unroll
;       for (int mb = 0; mb < MB; ++mb)
; #pragma unroll
;         for (int nb = 0; nb < 2; ++nb)
;           acc[mb][nb] = SWAP ? __builtin_amdgcn_mfma_f32_32x32x16_f16(bf[ks & 1][nb], af[ks & 1][mb], acc[mb][nb], 0, 0, 0)
;                              : __builtin_amdgcn_mfma_f32_32x32x16_f16(af[ks & 1][mb], bf[ks & 1][nb], acc[mb][nb], 0, 0, 0);
;       __builtin_amdgcn_s_setprio(0);
;       __builtin_amdgcn_sched_barrier(0);
;     }
;     cur = cur == 2 ? 0 : cur + 1;
;   }
;   __syncthreads();
; template <int MB>
; DI void merge_tile(const Params& P, int layer, size_t row0, int nt, char* smem) {
;     ...
; #pragma unroll
;     for (int mb = 0; mb < MB; ++mb)
; #pragma unroll
;       for (int nb = 0; nb < 2; ++nb)
; #pragma unroll
;         for (int v = 0; v < 16; ++v) gpk[mb][nb][v >> 3][v & 7] = (h16)sigmoid_f(pa2[mb][nb][v]);
	ds_read_b128 v[32:35], v39 offset:8192
	ds_read_b128 v[72:75], v39 offset:12288
	v_add_u32_e32 v39, v88, v40
	v_add_u32_e32 v76, v88, v38
	v_add_u32_e32 v38, v89, v38
	ds_read_b128 v[40:43], v39
	ds_read_b128 v[76:79], v76
	ds_read_b128 v[80:83], v38 offset:8192
	ds_read_b128 v[84:87], v38 offset:12288
	s_setprio 1
	s_waitcnt lgkmcnt(3)
	v_mfma_f32_32x32x16_f16 v[16:31], v[32:35], v[40:43], v[16:31]
	v_mfma_f32_32x32x16_f16 v[0:15], v[72:75], v[40:43], v[0:15]
	s_setprio 0
	v_add_u32_e32 v32, v88, v37
	v_add_u32_e32 v37, v89, v37
	ds_read_b128 v[32:35], v32
	ds_read_b128 v[38:41], v37 offset:8192
	ds_read_b128 v[72:75], v37 offset:12288
	s_setprio 1
	s_waitcnt lgkmcnt(4)
	v_mfma_f32_32x32x16_f16 v[16:31], v[80:83], v[76:79], v[16:31]
	s_waitcnt lgkmcnt(3)
	v_mfma_f32_32x32x16_f16 v[0:15], v[84:87], v[76:79], v[0:15]
	s_setprio 0
	v_add_u32_e32 v37, v88, v36
	v_add_u32_e32 v36, v89, v36
	ds_read_b128 v[76:79], v37
	ds_read_b128 v[80:83], v36 offset:8192
	ds_read_b128 v[84:87], v36 offset:12288
	s_setprio 1
	s_waitcnt lgkmcnt(4)
	v_mfma_f32_32x32x16_f16 v[16:31], v[38:41], v[32:35], v[16:31]
	s_waitcnt lgkmcnt(3)
	v_mfma_f32_32x32x16_f16 v[0:15], v[72:75], v[32:35], v[0:15]
	s_setprio 0
	s_setprio 1
	s_waitcnt lgkmcnt(1)
	v_mfma_f32_32x32x16_f16 v[16:31], v[80:83], v[76:79], v[16:31]
	s_waitcnt lgkmcnt(0)
	v_mfma_f32_32x32x16_f16 v[0:15], v[84:87], v[76:79], v[0:15]
	s_setprio 0
	s_nop 8
	v_mul_f32_e32 v16, 0xbfb8aa3b, v16
	v_exp_f32_e32 v16, v16
	v_mul_f32_e32 v0, 0xbfb8aa3b, v0
	v_exp_f32_e32 v0, v0
	v_add_f32_e32 v16, 1.0, v16
	v_div_scale_f32 v32, s[2:3], v16, v16, 1.0
	v_rcp_f32_e32 v33, v32
	v_add_f32_e32 v0, 1.0, v0
	s_barrier
	v_fma_f32 v34, -v32, v33, 1.0
	v_fmac_f32_e32 v33, v34, v33
	v_div_scale_f32 v34, vcc, 1.0, v16, 1.0
	v_mul_f32_e32 v35, v34, v33
	v_fma_f32 v36, -v32, v35, v34
	v_fmac_f32_e32 v35, v36, v33
	v_fma_f32 v32, -v32, v35, v34
	v_div_fmas_f32 v32, v32, v33, v35
	v_div_fixup_f32 v16, v32, v16, 1.0
	v_cvt_f16_f32_e32 v112, v16
	v_mul_f32_e32 v16, 0xbfb8aa3b, v17
	v_exp_f32_e32 v98, v16
	v_mul_f32_e32 v16, 0xbfb8aa3b, v18
	v_exp_f32_e32 v99, v16
	v_mul_f32_e32 v16, 0xbfb8aa3b, v19
	v_exp_f32_e32 v96, v16
	v_mul_f32_e32 v16, 0xbfb8aa3b, v20
	v_exp_f32_e32 v97, v16
	v_mul_f32_e32 v16, 0xbfb8aa3b, v21
	v_exp_f32_e32 v94, v16
	v_mul_f32_e32 v16, 0xbfb8aa3b, v22
	v_exp_f32_e32 v95, v16
	v_mul_f32_e32 v16, 0xbfb8aa3b, v23
	v_exp_f32_e32 v92, v16
	v_mul_f32_e32 v16, 0xbfb8aa3b, v24
	v_exp_f32_e32 v93, v16
	v_mul_f32_e32 v16, 0xbfb8aa3b, v25
	v_exp_f32_e32 v90, v16
	v_mul_f32_e32 v16, 0xbfb8aa3b, v26
	v_exp_f32_e32 v91, v16
	v_mul_f32_e32 v16, 0xbfb8aa3b, v27
	v_exp_f32_e32 v88, v16
	v_mul_f32_e32 v16, 0xbfb8aa3b, v28
	v_exp_f32_e32 v89, v16
	v_mul_f32_e32 v16, 0xbfb8aa3b, v29
	v_exp_f32_e32 v86, v16
	v_mul_f32_e32 v16, 0xbfb8aa3b, v30
	v_exp_f32_e32 v87, v16
	v_mul_f32_e32 v16, 0xbfb8aa3b, v31
	v_exp_f32_e32 v16, v16
	s_nop 0
	v_add_f32_e32 v16, 1.0, v16
	v_div_scale_f32 v17, s[2:3], v16, v16, 1.0
	v_rcp_f32_e32 v18, v17
	s_nop 0
	v_fma_f32 v19, -v17, v18, 1.0
	v_fmac_f32_e32 v18, v19, v18
	v_div_scale_f32 v19, vcc, 1.0, v16, 1.0
	v_mul_f32_e32 v20, v19, v18
	v_fma_f32 v21, -v17, v20, v19
	v_fmac_f32_e32 v20, v21, v18
	v_fma_f32 v17, -v17, v20, v19
	v_div_fmas_f32 v17, v17, v18, v20
	v_div_fixup_f32 v16, v17, v16, 1.0
	v_cvt_f16_f32_e32 v110, v16
	v_div_scale_f32 v16, s[2:3], v0, v0, 1.0
	v_rcp_f32_e32 v17, v16
	s_nop 0
	v_fma_f32 v18, -v16, v17, 1.0
	v_fmac_f32_e32 v17, v18, v17
	v_div_scale_f32 v18, vcc, 1.0, v0, 1.0
	v_mul_f32_e32 v19, v18, v17
	v_fma_f32 v20, -v16, v19, v18
	v_fmac_f32_e32 v19, v20, v17
	v_fma_f32 v16, -v16, v19, v18
	v_div_fmas_f32 v16, v16, v17, v19
	v_div_fixup_f32 v0, v16, v0, 1.0
	v_cvt_f16_f32_e32 v111, v0
	v_mul_f32_e32 v0, 0xbfb8aa3b, v1
	v_exp_f32_e32 v84, v0
	v_mul_f32_e32 v0, 0xbfb8aa3b, v2
	v_exp_f32_e32 v85, v0
	v_mul_f32_e32 v0, 0xbfb8aa3b, v3
	v_exp_f32_e32 v82, v0
	v_mul_f32_e32 v0, 0xbfb8aa3b, v4
	v_exp_f32_e32 v83, v0
	v_mul_f32_e32 v0, 0xbfb8aa3b, v5
	v_exp_f32_e32 v80, v0
	v_mul_f32_e32 v0, 0xbfb8aa3b, v6
	v_exp_f32_e32 v81, v0
	v_mul_f32_e32 v0, 0xbfb8aa3b, v7
	v_exp_f32_e32 v78, v0
	v_mul_f32_e32 v0, 0xbfb8aa3b, v8
	v_exp_f32_e32 v79, v0
	v_mul_f32_e32 v0, 0xbfb8aa3b, v9
	v_exp_f32_e32 v76, v0
	v_mul_f32_e32 v0, 0xbfb8aa3b, v10
	v_exp_f32_e32 v77, v0
	v_mul_f32_e32 v0, 0xbfb8aa3b, v11
	v_exp_f32_e32 v74, v0
	v_mul_f32_e32 v0, 0xbfb8aa3b, v12
	v_exp_f32_e32 v75, v0
	v_mul_f32_e32 v0, 0xbfb8aa3b, v13
	v_exp_f32_e32 v72, v0
	v_mul_f32_e32 v0, 0xbfb8aa3b, v14
	v_exp_f32_e32 v73, v0
	v_mul_f32_e32 v0, 0xbfb8aa3b, v15
	v_exp_f32_e32 v0, v0
	s_nop 0
	v_add_f32_e32 v0, 1.0, v0
	v_div_scale_f32 v1, s[2:3], v0, v0, 1.0
	v_rcp_f32_e32 v2, v1
	s_add_u32 s2, s87, s0
	s_addc_u32 s3, s96, 0
	s_or_b32 s0, s51, s81
	v_fma_f32 v3, -v1, v2, 1.0
	v_fmac_f32_e32 v2, v3, v2
	v_div_scale_f32 v3, vcc, 1.0, v0, 1.0
	v_mul_f32_e32 v4, v3, v2
	v_fma_f32 v5, -v1, v4, v3
	v_fmac_f32_e32 v4, v5, v2
	v_fma_f32 v1, -v1, v4, v3
	v_div_fmas_f32 v1, v1, v2, v4
	v_div_fixup_f32 v0, v1, v0, 1.0
	v_mov_b32_e32 v2, v208
	v_cvt_f16_f32_e32 v109, v0
	s_mul_i32 s84, s0, 0x240
	v_ashrrev_i32_e32 v0, 3, v2
	v_bfe_u32 v1, v2, 3, 3
	v_and_or_b32 v1, v0, -8, v1
	v_lshrrev_b32_e32 v3, 1, v1
	v_xor_b32_e32 v3, v3, v2
	v_mul_lo_u32 v4, v1, s13
	v_lshlrev_b32_e32 v3, 3, v3
	v_and_or_b32 v3, v3, 56, v4
	v_lshlrev_b32_e32 v128, 1, v3
	v_lshlrev_b32_e32 v3, 4, v2
	v_and_b32_e32 v3, 0x70, v3
	v_lshl_or_b32 v140, v1, 7, v3
	v_and_b32_e32 v1, 31, v2
	s_lshl_b64 s[0:1], s[84:85], 1
	v_and_or_b32 v4, v0, s16, v1
	v_lshlrev_b32_e32 v0, 7, v2
	v_add_u32_e32 v118, 0, v140
	s_add_u32 s24, s74, s0
	v_and_b32_e32 v5, 0x6f80, v0
; DI void wait_vm0() { asm volatile("s_waitcnt vmcnt(0)" ::: "memory"); }
; template <int MB, bool SWAP>
; DI void gemm_kloop(f32x16 (&acc)[MB][2], const h16* __restrict__ A, int lda, const h16* __restrict__ B, int ldb, int K, char* lds) {
;     ...
;   const int tid = otid(), w = tid >> 6, lane = tid & 63;
;   const int wr = w >> 2, wc = w & 3;
;   const int lrow = w * 8 + (lane >> 3), pch = lane & 7;
;   const int gch = pch ^ ((lrow >> 1) & 7);
;   const unsigned voa = (unsigned)(lrow * lda + gch * 8) * 2u, vob = (unsigned)(lrow * ldb + gch * 8) * 2u;
;   const int lofs = lrow * 128 + pch * 16;
;   const int r32 = lane & 31, hh = lane >> 5, sw = (r32 >> 1) & 7;
;   const int a_rd = (wr * 32 * MB + r32) * 128;
;   const int b_rd = A_BYTES + (wc * 64 + r32) * 128;
;   const int nk = K >> 6;
;   constexpr int NP = MB + 4;
;   auto piece = [&](int p, int kt, int buf) {
;     char* s = lds + buf * STAGE;
;     if (p < MB) __builtin_amdgcn_global_load_lds((const unsigned*)((const char*)(A + (size_t)p * 64 * lda + kt * 64) + voa), (unsigned*)(s + p * 8192 + lofs), 16, 0, 0);
;     else __builtin_amdgcn_global_load_lds((const unsigned*)((const char*)(B + (size_t)(p - MB) * 64 * ldb + kt * 64) + vob), (unsigned*)(s + A_BYTES + (p - MB) * 8192 + lofs), 16, 0, 0);
;   };
;   wait_vm0();
; #pragma unroll
;   for (int p = 0; p < NP; ++p) piece(p, 0, 0);
; #pragma unroll
;   for (int p = 0; p < NP; ++p) piece(p, 1, 1);
;   int cur = 0;
;   for (int kt = 0; kt < nk; ++kt) {
;     if (kt + 1 < nk) { if (MB == 2) asm volatile("s_waitcnt vmcnt(6)" ::: "memory"); else asm volatile("s_waitcnt vmcnt(5)" ::: "memory"); }
;     else wait_vm0();
;     __syncthreads();
;     const char* s = lds + cur * STAGE;
;     const int nbuf = cur == 0 ? 2 : cur - 1;
;     const bool more = kt + 2 < nk;
;     half8 af[2][MB], bf[2][2];
; #pragma unroll
;     for (int mb = 0; mb < MB; ++mb) af[0][mb] = *(const half8*)(s + a_rd + mb * 4096 + (((0 + hh) ^ sw) * 16));
; #pragma unroll
;     for (int nb = 0; nb < 2; ++nb) bf[0][nb] = *(const half8*)(s + b_rd + nb * 4096 + (((0 + hh) ^ sw) * 16));
; #pragma unroll
;     for (int ks = 0; ks < 4; ++ks) {
;       if (ks < 3) {
; #pragma unroll
;         for (int mb = 0; mb < MB; ++mb) af[(ks + 1) & 1][mb] = *(const half8*)(s + a_rd + mb * 4096 + (((2 * (ks + 1) + hh) ^ sw) * 16));
; #pragma unroll
	v_readfirstlane_b32 s0, v118
	v_add_u32_e32 v0, 0x2000, v118
	s_addc_u32 s25, s75, s1
	s_nop 0
	s_mov_b32 m0, s0
	v_readfirstlane_b32 s45, v0
	v_add_u32_e32 v6, 0x4000, v118
	v_lshl_add_u64 v[100:101], s[24:25], 0, v[128:129]
	v_lshl_add_u64 v[102:103], s[2:3], 0, v[128:129]
	global_load_lds_dwordx4 v128, s[2:3]
	s_mov_b32 m0, s45
	s_mov_b64 s[2:3], 0x12000
	v_readfirstlane_b32 s44, v6
	v_add_u32_e32 v6, 0x6000, v118
	global_load_lds_dwordx4 v128, s[24:25]
	v_lshl_add_u64 v[0:1], v[100:101], 0, s[2:3]
	s_mov_b32 m0, s44
	s_mov_b64 s[2:3], 0x24000
	v_readfirstlane_b32 s77, v6
	v_add_u32_e32 v6, 0x8000, v118
	global_load_lds_dwordx4 v[0:1], off
	v_lshl_add_u64 v[0:1], v[100:101], 0, s[2:3]
	s_mov_b32 m0, s77
	s_mov_b64 s[2:3], 0x36000
	v_readfirstlane_b32 s50, v6
	v_lshlrev_b32_e32 v120, 7, v4
	v_add_u32_e32 v4, 0xa000, v118
	global_load_lds_dwordx4 v[0:1], off
	v_lshl_add_u64 v[0:1], v[100:101], 0, s[2:3]
	s_mov_b32 m0, s50
	v_readfirstlane_b32 s84, v4
	v_add_u32_e32 v4, 0xc000, v118
	global_load_lds_dwordx4 v[0:1], off
	v_lshl_add_u64 v[0:1], v[102:103], 0, s[22:23]
	s_mov_b32 m0, s84
	v_readfirstlane_b32 s51, v4
	global_load_lds_dwordx4 v[0:1], off
	v_lshl_add_u64 v[0:1], v[100:101], 0, s[22:23]
	s_mov_b32 m0, s51
	s_mov_b64 s[2:3], 0x12080
	v_add_u32_e32 v4, 0xe000, v118
	global_load_lds_dwordx4 v[0:1], off
	v_lshl_add_u64 v[0:1], v[100:101], 0, s[2:3]
	v_readfirstlane_b32 s3, v4
	v_add_u32_e32 v4, s8, v140
	s_mov_b32 m0, s3
	s_mov_b64 s[24:25], 0x24080
	v_readfirstlane_b32 s1, v4
	v_add_u32_e32 v4, s9, v140
	global_load_lds_dwordx4 v[0:1], off
	v_lshl_add_u64 v[0:1], v[100:101], 0, s[24:25]
	s_mov_b32 m0, s1
	s_mov_b64 s[24:25], 0x36080
	v_readfirstlane_b32 s2, v4
	v_lshrrev_b32_e32 v3, 1, v2
	v_bfe_u32 v6, v2, 5, 1
	global_load_lds_dwordx4 v[0:1], off
	v_lshl_add_u64 v[0:1], v[100:101], 0, s[24:25]
	s_mov_b32 m0, s2
	v_add_u32_e32 v16, s79, v140
	global_load_lds_dwordx4 v[0:1], off
	v_bfe_u32 v0, v2, 1, 3
	v_bitop3_b32 v1, v6, v3, 7 bitop3:0x78
	v_lshlrev_b32_e32 v128, 4, v1
	v_bitop3_b32 v1, v6, v0, 2 bitop3:0x36
	v_lshlrev_b32_e32 v141, 4, v1
	v_add_u32_e32 v142, 0, v120
	v_add_u32_e32 v143, 0, v5
	v_add_u32_e32 v126, s10, v140
	v_readfirstlane_b32 s33, v16
	v_bitop3_b32 v1, v6, v0, 4 bitop3:0x36
	v_bitop3_b32 v0, v6, v0, 6 bitop3:0x36
	v_add_u32_e32 v113, v143, v128
	v_add_u32_e32 v114, v142, v128
	v_add_u32_e32 v115, v142, v141
	v_add_u32_e32 v116, v143, v141
	v_lshl_add_u64 v[14:15], v[102:103], 0, s[30:31]
	s_mov_b32 m0, s33
	v_readfirstlane_b32 s1, v126
	v_add_u32_e32 v117, 0x2000, v5
	v_lshlrev_b32_e32 v121, 4, v1
	v_lshlrev_b32_e32 v119, 4, v0
	s_waitcnt vmcnt(5)
	s_waitcnt lgkmcnt(0)
	s_barrier
	ds_read_b128 v[0:3], v113 offset:8192
	ds_read_b128 v[4:7], v113 offset:12288
	ds_read_b128 v[8:11], v114
	ds_read_b128 v[32:35], v115
	ds_read_b128 v[40:43], v116 offset:8192
	ds_read_b128 v[36:39], v116 offset:12288
	v_lshl_add_u64 v[12:13], v[100:101], 0, s[30:31]
	global_load_lds_dwordx4 v[14:15], off
	s_mov_b32 m0, s1
	s_nop 0
	global_load_lds_dwordx4 v[12:13], off
	s_setprio 1
	s_waitcnt lgkmcnt(0)
	v_mfma_f32_32x32x16_f16 v[16:31], v[0:3], v[8:11], 0
	v_mfma_f32_32x32x16_f16 v[0:15], v[4:7], v[8:11], 0
	s_setprio 0
	s_mov_b64 s[24:25], 0x24100
	v_add_u32_e32 v146, 0x4000, v126
	v_lshl_add_u64 v[126:127], v[100:101], 0, s[24:25]
	s_add_i32 s24, 0, 0x18000
	v_add_u32_e32 v147, s24, v140
	v_add_u32_e32 v144, v142, v121
	v_readfirstlane_b32 s78, v147
	v_lshl_add_u64 v[138:139], v[100:101], 0, s[92:93]
	s_mov_b32 m0, s78
	v_readfirstlane_b32 s24, v146
	v_add_u32_e32 v145, v143, v121
	ds_read_b128 v[122:125], v144
	ds_read_b128 v[130:133], v145 offset:8192
	ds_read_b128 v[134:137], v145 offset:12288
	global_load_lds_dwordx4 v[138:139], off
	s_mov_b32 m0, s24
	s_nop 0
	global_load_lds_dwordx4 v[126:127], off
	s_setprio 1
	v_mfma_f32_32x32x16_f16 v[16:31], v[40:43], v[32:35], v[16:31]
	v_mfma_f32_32x32x16_f16 v[0:15], v[36:39], v[32:35], v[0:15]
	s_setprio 0
	v_add_u32_e32 v138, s17, v140
	s_mov_b64 s[52:53], 0x36100
	v_readfirstlane_b32 s25, v138
	v_add_u32_e32 v142, v142, v119
	v_lshl_add_u64 v[126:127], v[100:101], 0, s[52:53]
	s_mov_b32 m0, s25
	v_add_u32_e32 v143, v143, v119
	ds_read_b128 v[32:35], v142
	ds_read_b128 v[36:39], v143 offset:8192
	ds_read_b128 v[40:43], v143 offset:12288
	global_load_lds_dwordx4 v[126:127], off
	s_setprio 1
	s_waitcnt lgkmcnt(0)
	v_mfma_f32_32x32x16_f16 v[16:31], v[130:133], v[122:125], v[16:31]
	v_mfma_f32_32x32x16_f16 v[0:15], v[134:137], v[122:125], v[0:15]
	s_setprio 0
	s_setprio 1
	v_mfma_f32_32x32x16_f16 v[16:31], v[36:39], v[32:35], v[16:31]
	v_mfma_f32_32x32x16_f16 v[0:15], v[40:43], v[32:35], v[0:15]
	s_setprio 0
	s_mov_b64 s[52:53], 0x180
	s_mov_b32 m0, s0
	v_lshl_add_u64 v[138:139], v[102:103], 0, s[52:53]
	s_waitcnt vmcnt(5)
	s_waitcnt lgkmcnt(0)
	s_barrier
; DI void wait_vm0() { asm volatile("s_waitcnt vmcnt(0)" ::: "memory"); }
; template <int MB, bool SWAP>
; DI void gemm_kloop(f32x16 (&acc)[MB][2], const h16* __restrict__ A, int lda, const h16* __restrict__ B, int ldb, int K, char* lds) {
;     ...
;   for (int kt = 0; kt < nk; ++kt) {
;     if (kt + 1 < nk) { if (MB == 2) asm volatile("s_waitcnt vmcnt(6)" ::: "memory"); else asm volatile("s_waitcnt vmcnt(5)" ::: "memory"); }
;     else wait_vm0();
;     __syncthreads();
;     const char* s = lds + cur * STAGE;
;     const int nbuf = cur == 0 ? 2 : cur - 1;
;     const bool more = kt + 2 < nk;
;     half8 af[2][MB], bf[2][2];
; #pragma unroll
;     for (int mb = 0; mb < MB; ++mb) af[0][mb] = *(const half8*)(s + a_rd + mb * 4096 + (((0 + hh) ^ sw) * 16));
; #pragma unroll
;     for (int nb = 0; nb < 2; ++nb) bf[0][nb] = *(const half8*)(s + b_rd + nb * 4096 + (((0 + hh) ^ sw) * 16));
; #pragma unroll
;     for (int ks = 0; ks < 4; ++ks) {
;       if (ks < 3) {
; #pragma unroll
;         for (int mb = 0; mb < MB; ++mb) af[(ks + 1) & 1][mb] = *(const half8*)(s + a_rd + mb * 4096 + (((2 * (ks + 1) + hh) ^ sw) * 16));
; #pragma unroll
;         for (int nb = 0; nb < 2; ++nb) bf[(ks + 1) & 1][nb] = *(const half8*)(s + b_rd + nb * 4096 + (((2 * (ks + 1) + hh) ^ sw) * 16));
;       }
;       if (more) {
;         if (2 * ks < NP) piece(2 * ks, kt + 2, nbuf);
;         if (2 * ks + 1 < NP) piece(2 * ks + 1, kt + 2, nbuf);
;       }
;       __builtin_amdgcn_sched_barrier(0);
;       __builtin_amdgcn_s_setprio(1);
; #pragma unroll
;       for (int mb = 0; mb < MB; ++mb)
; #pragma unroll
;         for (int nb = 0; nb < 2; ++nb)
;           acc[mb][nb] = SWAP ? __builtin_amdgcn_mfma_f32_32x32x16_f16(bf[ks & 1][nb], af[ks & 1][mb], acc[mb][nb], 0, 0, 0)
;                              : __builtin_amdgcn_mfma_f32_32x32x16_f16(af[ks & 1][mb], bf[ks & 1][nb], acc[mb][nb], 0, 0, 0);
;       __builtin_amdgcn_s_setprio(0);
;       __builtin_amdgcn_sched_barrier(0);
;     }
	ds_read_b128 v[32:35], v113 offset:49152
	ds_read_b128 v[36:39], v113 offset:53248
	ds_read_b128 v[40:43], v114 offset:40960
	ds_read_b128 v[122:125], v115 offset:40960
	ds_read_b128 v[130:133], v116 offset:49152
	ds_read_b128 v[134:137], v116 offset:53248
	v_lshl_add_u64 v[126:127], v[100:101], 0, s[52:53]
	global_load_lds_dwordx4 v[138:139], off
	s_mov_b32 m0, s45
	s_nop 0
	global_load_lds_dwordx4 v[126:127], off
	s_setprio 1
	s_waitcnt lgkmcnt(0)
	v_mfma_f32_32x32x16_f16 v[16:31], v[32:35], v[40:43], v[16:31]
	v_mfma_f32_32x32x16_f16 v[0:15], v[36:39], v[40:43], v[0:15]
	s_setprio 0
	s_mov_b64 s[52:53], 0x24180
	v_lshl_add_u64 v[126:127], v[100:101], 0, s[52:53]
	s_mov_b64 s[52:53], 0x12180
	s_mov_b32 m0, s44
	v_lshl_add_u64 v[138:139], v[100:101], 0, s[52:53]
	ds_read_b128 v[32:35], v144 offset:40960
	ds_read_b128 v[36:39], v145 offset:49152
	ds_read_b128 v[40:43], v145 offset:53248
	global_load_lds_dwordx4 v[138:139], off
	s_mov_b32 m0, s77
	s_nop 0
	global_load_lds_dwordx4 v[126:127], off
	s_setprio 1
	v_mfma_f32_32x32x16_f16 v[16:31], v[130:133], v[122:125], v[16:31]
	v_mfma_f32_32x32x16_f16 v[0:15], v[134:137], v[122:125], v[0:15]
	s_setprio 0
	s_mov_b64 s[52:53], 0x36180
	v_lshl_add_u64 v[126:127], v[100:101], 0, s[52:53]
	s_mov_b32 m0, s50
	ds_read_b128 v[122:125], v142 offset:40960
	ds_read_b128 v[130:133], v143 offset:49152
	ds_read_b128 v[134:137], v143 offset:53248
	global_load_lds_dwordx4 v[126:127], off
	s_setprio 1
	s_waitcnt lgkmcnt(0)
	v_mfma_f32_32x32x16_f16 v[16:31], v[36:39], v[32:35], v[16:31]
	v_mfma_f32_32x32x16_f16 v[0:15], v[40:43], v[32:35], v[0:15]
	s_setprio 0
	s_setprio 1
	v_mfma_f32_32x32x16_f16 v[16:31], v[130:133], v[122:125], v[16:31]
	v_mfma_f32_32x32x16_f16 v[0:15], v[134:137], v[122:125], v[0:15]
	s_setprio 0
	v_add_u32_e32 v140, s79, v120
	s_mov_b64 s[52:53], 0x200
	s_mov_b32 m0, s84
	v_add3_u32 v146, s79, v128, v117
	v_add_u32_e32 v128, v140, v128
	v_add_u32_e32 v147, v140, v141
	v_add3_u32 v141, s79, v141, v117
	v_lshl_add_u64 v[138:139], v[102:103], 0, s[52:53]
	s_waitcnt vmcnt(5)
	s_waitcnt lgkmcnt(0)
	s_barrier
	ds_read_b128 v[32:35], v146
	ds_read_b128 v[36:39], v146 offset:4096
	ds_read_b128 v[40:43], v128
	ds_read_b128 v[122:125], v147
	ds_read_b128 v[130:133], v141
	ds_read_b128 v[134:137], v141 offset:4096
	v_lshl_add_u64 v[126:127], v[100:101], 0, s[52:53]
	global_load_lds_dwordx4 v[138:139], off
	s_mov_b32 m0, s51
	s_nop 0
	global_load_lds_dwordx4 v[126:127], off
	s_setprio 1
	s_waitcnt lgkmcnt(0)
	v_mfma_f32_32x32x16_f16 v[16:31], v[32:35], v[40:43], v[16:31]
	v_mfma_f32_32x32x16_f16 v[0:15], v[36:39], v[40:43], v[0:15]
	s_setprio 0
	s_mov_b64 s[52:53], 0x24200
	v_add_u32_e32 v138, v140, v121
	v_add3_u32 v139, s79, v121, v117
	v_add_u32_e32 v118, 0x10000, v118
	v_lshl_add_u64 v[120:121], v[100:101], 0, s[52:53]
	s_mov_b64 s[52:53], 0x12200
	s_mov_b32 m0, s3
	v_lshl_add_u64 v[126:127], v[100:101], 0, s[52:53]
	v_readfirstlane_b32 s52, v118
	ds_read_b128 v[32:35], v138
	ds_read_b128 v[36:39], v139
	ds_read_b128 v[40:43], v139 offset:4096
	global_load_lds_dwordx4 v[126:127], off
	s_mov_b32 m0, s52
	s_nop 0
	global_load_lds_dwordx4 v[120:121], off
	s_setprio 1
	v_mfma_f32_32x32x16_f16 v[16:31], v[130:133], v[122:125], v[16:31]
	v_mfma_f32_32x32x16_f16 v[0:15], v[134:137], v[122:125], v[0:15]
	s_setprio 0
	s_mov_b64 s[54:55], 0x36200
	v_add_u32_e32 v136, v140, v119
	v_lshl_add_u64 v[126:127], v[100:101], 0, s[54:55]
	s_mov_b32 m0, s2
	v_add3_u32 v117, s79, v119, v117
	ds_read_b128 v[118:121], v136
	ds_read_b128 v[122:125], v117
	ds_read_b128 v[130:133], v117 offset:4096
	global_load_lds_dwordx4 v[126:127], off
	s_setprio 1
	s_waitcnt lgkmcnt(0)
	v_mfma_f32_32x32x16_f16 v[16:31], v[36:39], v[32:35], v[16:31]
	v_mfma_f32_32x32x16_f16 v[0:15], v[40:43], v[32:35], v[0:15]
	s_setprio 0
	s_setprio 1
	v_mfma_f32_32x32x16_f16 v[16:31], v[122:125], v[118:121], v[16:31]
	v_mfma_f32_32x32x16_f16 v[0:15], v[130:133], v[118:121], v[0:15]
	s_setprio 0
	s_mov_b64 s[54:55], 0x280
	s_mov_b32 m0, s33
	v_lshl_add_u64 v[134:135], v[102:103], 0, s[54:55]
	s_waitcnt vmcnt(5)
	s_waitcnt lgkmcnt(0)
	s_barrier
	ds_read_b128 v[32:35], v113 offset:8192
	ds_read_b128 v[36:39], v113 offset:12288
	ds_read_b128 v[40:43], v114
	ds_read_b128 v[118:121], v115
	ds_read_b128 v[122:125], v116 offset:8192
	ds_read_b128 v[130:133], v116 offset:12288
	v_lshl_add_u64 v[126:127], v[100:101], 0, s[54:55]
	global_load_lds_dwordx4 v[134:135], off
	s_mov_b32 m0, s1
	s_nop 0
	global_load_lds_dwordx4 v[126:127], off
	s_setprio 1
	s_waitcnt lgkmcnt(0)
	v_mfma_f32_32x32x16_f16 v[16:31], v[32:35], v[40:43], v[16:31]
	v_mfma_f32_32x32x16_f16 v[0:15], v[36:39], v[40:43], v[0:15]
	s_setprio 0
	s_mov_b64 s[54:55], 0x24280
	v_lshl_add_u64 v[126:127], v[100:101], 0, s[54:55]
	s_mov_b64 s[54:55], 0x12280
	s_mov_b32 m0, s78
	v_lshl_add_u64 v[134:135], v[100:101], 0, s[54:55]
	ds_read_b128 v[32:35], v144
	ds_read_b128 v[36:39], v145 offset:8192
	ds_read_b128 v[40:43], v145 offset:12288
	global_load_lds_dwordx4 v[134:135], off
	s_mov_b32 m0, s24
	s_nop 0
	global_load_lds_dwordx4 v[126:127], off
	s_setprio 1
	v_mfma_f32_32x32x16_f16 v[16:31], v[122:125], v[118:121], v[16:31]
	v_mfma_f32_32x32x16_f16 v[0:15], v[130:133], v[118:121], v[0:15]
	s_setprio 0
	s_mov_b64 s[54:55], 0x36280
	v_lshl_add_u64 v[126:127], v[100:101], 0, s[54:55]
	s_mov_b32 m0, s25
	ds_read_b128 v[118:121], v142
	ds_read_b128 v[122:125], v143 offset:8192
	ds_read_b128 v[130:133], v143 offset:12288
	global_load_lds_dwordx4 v[126:127], off
	s_setprio 1
	s_waitcnt lgkmcnt(0)
	v_mfma_f32_32x32x16_f16 v[16:31], v[36:39], v[32:35], v[16:31]
	v_mfma_f32_32x32x16_f16 v[0:15], v[40:43], v[32:35], v[0:15]
	s_setprio 0
	s_setprio 1
	v_mfma_f32_32x32x16_f16 v[16:31], v[122:125], v[118:121], v[16:31]
	v_mfma_f32_32x32x16_f16 v[0:15], v[130:133], v[118:121], v[0:15]
	s_setprio 0
	s_mov_b32 m0, s0
	s_mov_b64 s[0:1], 0x300
	v_lshl_add_u64 v[134:135], v[102:103], 0, s[0:1]
	s_waitcnt vmcnt(5)
	s_waitcnt lgkmcnt(0)
	s_barrier
; DI void wait_vm0() { asm volatile("s_waitcnt vmcnt(0)" ::: "memory"); }
; template <int MB, bool SWAP>
; DI void gemm_kloop(f32x16 (&acc)[MB][2], const h16* __restrict__ A, int lda, const h16* __restrict__ B, int ldb, int K, char* lds) {
;     ...
;   for (int kt = 0; kt < nk; ++kt) {
;     if (kt + 1 < nk) { if (MB == 2) asm volatile("s_waitcnt vmcnt(6)" ::: "memory"); else asm volatile("s_waitcnt vmcnt(5)" ::: "memory"); }
;     else wait_vm0();
;     __syncthreads();
;     const char* s = lds + cur * STAGE;
;     const int nbuf = cur == 0 ? 2 : cur - 1;
;     const bool more = kt + 2 < nk;
;     half8 af[2][MB], bf[2][2];
; #pragma unroll
;     for (int mb = 0; mb < MB; ++mb) af[0][mb] = *(const half8*)(s + a_rd + mb * 4096 + (((0 + hh) ^ sw) * 16));
; #pragma unroll
;     for (int nb = 0; nb < 2; ++nb) bf[0][nb] = *(const half8*)(s + b_rd + nb * 4096 + (((0 + hh) ^ sw) * 16));
; #pragma unroll
;     for (int ks = 0; ks < 4; ++ks) {
;       if (ks < 3) {
; #pragma unroll
;         for (int mb = 0; mb < MB; ++mb) af[(ks + 1) & 1][mb] = *(const half8*)(s + a_rd + mb * 4096 + (((2 * (ks + 1) + hh) ^ sw) * 16));
; #pragma unroll
;         for (int nb = 0; nb < 2; ++nb) bf[(ks + 1) & 1][nb] = *(const half8*)(s + b_rd + nb * 4096 + (((2 * (ks + 1) + hh) ^ sw) * 16));
;       }
;       if (more) {
;         if (2 * ks < NP) piece(2 * ks, kt + 2, nbuf);
;         if (2 * ks + 1 < NP) piece(2 * ks + 1, kt + 2, nbuf);
;       }
;       __builtin_amdgcn_sched_barrier(0);
;       __builtin_amdgcn_s_setprio(1);
; #pragma unroll
;       for (int mb = 0; mb < MB; ++mb)
; #pragma unroll
;         for (int nb = 0; nb < 2; ++nb)
;           acc[mb][nb] = SWAP ? __builtin_amdgcn_mfma_f32_32x32x16_f16(bf[ks & 1][nb], af[ks & 1][mb], acc[mb][nb], 0, 0, 0)
;                              : __builtin_amdgcn_mfma_f32_32x32x16_f16(af[ks & 1][mb], bf[ks & 1][nb], acc[mb][nb], 0, 0, 0);
;       __builtin_amdgcn_s_setprio(0);
;       __builtin_amdgcn_sched_barrier(0);
;     }
;     cur = cur == 2 ? 0 : cur + 1;
;   }
;   __syncthreads();
	ds_read_b128 v[32:35], v113 offset:49152
	ds_read_b128 v[36:39], v113 offset:53248
	ds_read_b128 v[40:43], v114 offset:40960
	ds_read_b128 v[118:121], v115 offset:40960
	ds_read_b128 v[122:125], v116 offset:49152
	ds_read_b128 v[130:133], v116 offset:53248
	v_lshl_add_u64 v[126:127], v[100:101], 0, s[0:1]
	global_load_lds_dwordx4 v[134:135], off
	s_mov_b32 m0, s45
	s_nop 0
	global_load_lds_dwordx4 v[126:127], off
	s_setprio 1
	s_waitcnt lgkmcnt(0)
	v_mfma_f32_32x32x16_f16 v[16:31], v[32:35], v[40:43], v[16:31]
	v_mfma_f32_32x32x16_f16 v[0:15], v[36:39], v[40:43], v[0:15]
	s_setprio 0
	s_mov_b64 s[0:1], 0x24300
	v_lshl_add_u64 v[126:127], v[100:101], 0, s[0:1]
	s_mov_b64 s[0:1], 0x12300
	s_mov_b32 m0, s44
	v_lshl_add_u64 v[134:135], v[100:101], 0, s[0:1]
	ds_read_b128 v[32:35], v144 offset:40960
	ds_read_b128 v[36:39], v145 offset:49152
	ds_read_b128 v[40:43], v145 offset:53248
	global_load_lds_dwordx4 v[134:135], off
	s_mov_b32 m0, s77
	s_nop 0
	global_load_lds_dwordx4 v[126:127], off
	s_setprio 1
	v_mfma_f32_32x32x16_f16 v[16:31], v[122:125], v[118:121], v[16:31]
	v_mfma_f32_32x32x16_f16 v[0:15], v[130:133], v[118:121], v[0:15]
	s_setprio 0
	s_mov_b64 s[0:1], 0x36300
	v_lshl_add_u64 v[126:127], v[100:101], 0, s[0:1]
	s_mov_b32 m0, s50
	ds_read_b128 v[118:121], v142 offset:40960
	ds_read_b128 v[122:125], v143 offset:49152
	ds_read_b128 v[130:133], v143 offset:53248
	global_load_lds_dwordx4 v[126:127], off
	s_setprio 1
	s_waitcnt lgkmcnt(0)
	v_mfma_f32_32x32x16_f16 v[16:31], v[36:39], v[32:35], v[16:31]
	v_mfma_f32_32x32x16_f16 v[0:15], v[40:43], v[32:35], v[0:15]
	s_setprio 0
	s_setprio 1
	v_mfma_f32_32x32x16_f16 v[16:31], v[122:125], v[118:121], v[16:31]
	v_mfma_f32_32x32x16_f16 v[0:15], v[130:133], v[118:121], v[0:15]
	s_setprio 0
	s_mov_b64 s[0:1], 0x380
	s_mov_b32 m0, s84
	v_lshl_add_u64 v[102:103], v[102:103], 0, s[0:1]
	s_waitcnt vmcnt(5)
	s_waitcnt lgkmcnt(0)
	s_barrier
	ds_read_b128 v[32:35], v146
	ds_read_b128 v[36:39], v146 offset:4096
	ds_read_b128 v[40:43], v128
	ds_read_b128 v[118:121], v147
	ds_read_b128 v[122:125], v141
	ds_read_b128 v[130:133], v141 offset:4096
	v_lshl_add_u64 v[126:127], v[100:101], 0, s[0:1]
	global_load_lds_dwordx4 v[102:103], off
	s_mov_b32 m0, s51
	s_nop 0
	global_load_lds_dwordx4 v[126:127], off
	s_setprio 1
	s_waitcnt lgkmcnt(0)
	v_mfma_f32_32x32x16_f16 v[16:31], v[32:35], v[40:43], v[16:31]
	v_mfma_f32_32x32x16_f16 v[0:15], v[36:39], v[40:43], v[0:15]
	s_setprio 0
	s_mov_b64 s[0:1], 0x24380
	v_lshl_add_u64 v[102:103], v[100:101], 0, s[0:1]
	s_mov_b64 s[0:1], 0x12380
	s_mov_b32 m0, s3
	v_lshl_add_u64 v[126:127], v[100:101], 0, s[0:1]
	ds_read_b128 v[32:35], v138
	ds_read_b128 v[36:39], v139
	ds_read_b128 v[40:43], v139 offset:4096
	global_load_lds_dwordx4 v[126:127], off
	s_mov_b32 m0, s52
	s_nop 0
	global_load_lds_dwordx4 v[102:103], off
	s_setprio 1
	v_mfma_f32_32x32x16_f16 v[16:31], v[122:125], v[118:121], v[16:31]
	v_mfma_f32_32x32x16_f16 v[0:15], v[130:133], v[118:121], v[0:15]
	s_setprio 0
	s_mov_b64 s[0:1], 0x36380
	v_lshl_add_u64 v[100:101], v[100:101], 0, s[0:1]
	s_mov_b32 m0, s2
	ds_read_b128 v[118:121], v136
	ds_read_b128 v[122:125], v117
	ds_read_b128 v[130:133], v117 offset:4096
	global_load_lds_dwordx4 v[100:101], off
	s_setprio 1
	s_waitcnt lgkmcnt(0)
	v_mfma_f32_32x32x16_f16 v[16:31], v[36:39], v[32:35], v[16:31]
	v_mfma_f32_32x32x16_f16 v[0:15], v[40:43], v[32:35], v[0:15]
	s_setprio 0
	s_setprio 1
	v_mfma_f32_32x32x16_f16 v[16:31], v[122:125], v[118:121], v[16:31]
	v_mfma_f32_32x32x16_f16 v[0:15], v[130:133], v[118:121], v[0:15]
	s_setprio 0
	s_waitcnt vmcnt(5)
	s_waitcnt lgkmcnt(0)
	s_barrier
	ds_read_b128 v[32:35], v116 offset:8192
	ds_read_b128 v[36:39], v116 offset:12288
	ds_read_b128 v[40:43], v115
	ds_read_b128 v[100:103], v114
	ds_read_b128 v[118:121], v113 offset:12288
	ds_read_b128 v[122:125], v113 offset:8192
	s_setprio 1
	s_waitcnt lgkmcnt(0)
	v_mfma_f32_32x32x16_f16 v[16:31], v[122:125], v[100:103], v[16:31]
	v_mfma_f32_32x32x16_f16 v[0:15], v[118:121], v[100:103], v[0:15]
	s_setprio 0
	ds_read_b128 v[100:103], v144
	ds_read_b128 v[118:121], v145 offset:8192
	ds_read_b128 v[122:125], v145 offset:12288
	s_setprio 1
	v_mfma_f32_32x32x16_f16 v[16:31], v[32:35], v[40:43], v[16:31]
	v_mfma_f32_32x32x16_f16 v[0:15], v[36:39], v[40:43], v[0:15]
	s_setprio 0
	ds_read_b128 v[32:35], v143 offset:12288
	ds_read_b128 v[36:39], v143 offset:8192
	ds_read_b128 v[40:43], v142
	s_setprio 1
	s_waitcnt lgkmcnt(4)
	v_mfma_f32_32x32x16_f16 v[16:31], v[118:121], v[100:103], v[16:31]
	s_waitcnt lgkmcnt(3)
	v_mfma_f32_32x32x16_f16 v[0:15], v[122:125], v[100:103], v[0:15]
	s_setprio 0
	s_setprio 1
	s_waitcnt lgkmcnt(0)
	v_mfma_f32_32x32x16_f16 v[16:31], v[36:39], v[40:43], v[16:31]
	v_mfma_f32_32x32x16_f16 v[0:15], v[32:35], v[40:43], v[0:15]
	s_setprio 0
	s_waitcnt vmcnt(0)
	s_barrier
; template <int MB, bool SWAP>
; DI void gemm_kloop(f32x16 (&acc)[MB][2], const h16* __restrict__ A, int lda, const h16* __restrict__ B, int ldb, int K, char* lds) {
;     ...
;   for (int kt = 0; kt < nk; ++kt) {
;     if (kt + 1 < nk) { if (MB == 2) asm volatile("s_waitcnt vmcnt(6)" ::: "memory"); else asm volatile("s_waitcnt vmcnt(5)" ::: "memory"); }
;     else wait_vm0();
;     __syncthreads();
;     const char* s = lds + cur * STAGE;
;     const int nbuf = cur == 0 ? 2 : cur - 1;
;     const bool more = kt + 2 < nk;
;     half8 af[2][MB], bf[2][2];
; #pragma unroll
;     for (int mb = 0; mb < MB; ++mb) af[0][mb] = *(const half8*)(s + a_rd + mb * 4096 + (((0 + hh) ^ sw) * 16));
; #pragma unroll
;     for (int nb = 0; nb < 2; ++nb) bf[0][nb] = *(const half8*)(s + b_rd + nb * 4096 + (((0 + hh) ^ sw) * 16));
; #pragma unroll
;     for (int ks = 0; ks < 4; ++ks) {
;       if (ks < 3) {
; #pragma unroll
;         for (int mb = 0; mb < MB; ++mb) af[(ks + 1) & 1][mb] = *(const half8*)(s + a_rd + mb * 4096 + (((2 * (ks + 1) + hh) ^ sw) * 16));
; #pragma unroll
;         for (int nb = 0; nb < 2; ++nb) bf[(ks + 1) & 1][nb] = *(const half8*)(s + b_rd + nb * 4096 + (((2 * (ks + 1) + hh) ^ sw) * 16));
;       }
;       if (more) {
;         if (2 * ks < NP) piece(2 * ks, kt + 2, nbuf);
;         if (2 * ks + 1 < NP) piece(2 * ks + 1, kt + 2, nbuf);
;       }
;       __builtin_amdgcn_sched_barrier(0);
;       __builtin_amdgcn_s_setprio(1);
; #pragma unroll
;       for (int mb = 0; mb < MB; ++mb)
; #pragma unroll
;         for (int nb = 0; nb < 2; ++nb)
;           acc[mb][nb] = SWAP ? __builtin_amdgcn_mfma_f32_32x32x16_f16(bf[ks & 1][nb], af[ks & 1][mb], acc[mb][nb], 0, 0, 0)
;                              : __builtin_amdgcn_mfma_f32_32x32x16_f16(af[ks & 1][mb], bf[ks & 1][nb], acc[mb][nb], 0, 0, 0);
;       __builtin_amdgcn_s_setprio(0);
;       __builtin_amdgcn_sched_barrier(0);
;     }
; template <int MB>
; DI void merge_tile(const Params& P, int layer, size_t row0, int nt, char* smem) {
;     ...
;         for (int v = 0; v < 16; ++v) gpk[mb][nb][v >> 3][v & 7] = (h16)sigmoid_f(pa2[mb][nb][v]);
;     zero_acc<MB>(pa2);
;     gemm_kloop<MB, true>(pa2, yn + row0 * LDY, LDY, wbrT + (size_t)(n * 1024 + nt * 256) * LDY, LDY, WB, smem);
; #pragma unroll
;     for (int mb = 0; mb < MB; ++mb)
; #pragma unroll
;       for (int nb = 0; nb < 2; ++nb)
; #pragma unroll
	ds_read_b128 v[32:35], v113 offset:49152
	ds_read_b128 v[36:39], v113 offset:53248
	ds_read_b128 v[40:43], v114 offset:40960
	ds_read_b128 v[100:103], v115 offset:40960
	ds_read_b128 v[118:121], v116 offset:49152
	ds_read_b128 v[114:117], v116 offset:53248
	s_setprio 1
	s_waitcnt lgkmcnt(3)
	v_mfma_f32_32x32x16_f16 v[16:31], v[32:35], v[40:43], v[16:31]
	v_mfma_f32_32x32x16_f16 v[0:15], v[36:39], v[40:43], v[0:15]
	s_setprio 0
	ds_read_b128 v[32:35], v144 offset:40960
	ds_read_b128 v[36:39], v145 offset:49152
	ds_read_b128 v[40:43], v145 offset:53248
	s_setprio 1
	s_waitcnt lgkmcnt(4)
	v_mfma_f32_32x32x16_f16 v[16:31], v[118:121], v[100:103], v[16:31]
	s_waitcnt lgkmcnt(3)
	v_mfma_f32_32x32x16_f16 v[0:15], v[114:117], v[100:103], v[0:15]
	s_setprio 0
	ds_read_b128 v[100:103], v142 offset:40960
	ds_read_b128 v[114:117], v143 offset:49152
	ds_read_b128 v[118:121], v143 offset:53248
	s_setprio 1
	s_waitcnt lgkmcnt(4)
	v_mfma_f32_32x32x16_f16 v[16:31], v[36:39], v[32:35], v[16:31]
	s_waitcnt lgkmcnt(3)
	v_mfma_f32_32x32x16_f16 v[0:15], v[40:43], v[32:35], v[0:15]
	s_setprio 0
	s_setprio 1
	s_waitcnt lgkmcnt(1)
	v_mfma_f32_32x32x16_f16 v[16:31], v[114:117], v[100:103], v[16:31]
	s_waitcnt lgkmcnt(0)
	v_mfma_f32_32x32x16_f16 v[0:15], v[118:121], v[100:103], v[0:15]
	s_setprio 0
	v_add_f32_e64 v32, v98, 1.0
	v_add_f32_e64 v33, v99, 1.0
	s_nop 6
	v_fma_mix_f32 v107, v16, v112, v107 op_sel_hi:[0,1,0]
	v_div_scale_f32 v16, s[0:1], v33, v33, 1.0
	v_rcp_f32_e32 v34, v16
	v_fma_mix_f32 v105, v0, v111, v105 op_sel_hi:[0,1,0]
	s_add_i32 s97, s97, 1
	s_add_u32 s42, s42, 0x220000
	v_fma_f32 v35, -v16, v34, 1.0
	v_fmac_f32_e32 v34, v35, v34
	v_div_scale_f32 v35, vcc, 1.0, v33, 1.0
	v_mul_f32_e32 v36, v35, v34
	v_fma_f32 v37, -v16, v36, v35
	v_fmac_f32_e32 v36, v37, v34
	v_fma_f32 v16, -v16, v36, v35
	v_div_fmas_f32 v16, v16, v34, v36
	v_div_fixup_f32 v16, v16, v33, 1.0
	v_div_scale_f32 v33, s[0:1], v32, v32, 1.0
	v_rcp_f32_e32 v34, v33
	s_addc_u32 s43, s43, 0
	v_fma_mix_f32 v106, v31, v110, v106 op_sel_hi:[0,1,0]
	v_fma_mix_f32 v104, v15, v109, v104 op_sel_hi:[0,1,0]
	v_fma_f32 v35, -v33, v34, 1.0
	v_fmac_f32_e32 v34, v35, v34
	v_div_scale_f32 v35, vcc, 1.0, v32, 1.0
	v_mul_f32_e32 v36, v35, v34
	v_fma_f32 v37, -v33, v36, v35
	v_fmac_f32_e32 v36, v37, v34
	v_fma_f32 v33, -v33, v36, v35
	v_div_fmas_f32 v33, v33, v34, v36
	v_div_fixup_f32 v32, v33, v32, 1.0
	v_cvt_pk_f16_f32 v16, v32, v16
	v_cvt_f32_f16_e32 v32, v16
	v_cvt_f32_f16_sdwa v33, v16 dst_sel:DWORD dst_unused:UNUSED_PAD src0_sel:WORD_1
	v_mov_b32_e32 v16, v17
	v_mov_b32_e32 v17, v18
	s_cmp_eq_u32 s97, 3
	v_pk_fma_f32 v[70:71], v[16:17], v[32:33], v[70:71]
	v_pk_add_f32 v[16:17], v[96:97], 1.0 op_sel_hi:[1,0]
	s_nop 0
	v_div_scale_f32 v18, s[0:1], v17, v17, 1.0
	v_rcp_f32_e32 v32, v18
	s_barrier
	v_fma_f32 v33, -v18, v32, 1.0
	v_fmac_f32_e32 v32, v33, v32
	v_div_scale_f32 v33, vcc, 1.0, v17, 1.0
	v_mul_f32_e32 v34, v33, v32
	v_fma_f32 v35, -v18, v34, v33
	v_fmac_f32_e32 v34, v35, v32
	v_fma_f32 v18, -v18, v34, v33
	v_div_fmas_f32 v18, v18, v32, v34
	v_div_fixup_f32 v17, v18, v17, 1.0
	v_div_scale_f32 v18, s[0:1], v16, v16, 1.0
	v_rcp_f32_e32 v32, v18
	s_nop 0
	v_fma_f32 v33, -v18, v32, 1.0
	v_fmac_f32_e32 v32, v33, v32
	v_div_scale_f32 v33, vcc, 1.0, v16, 1.0
	v_mul_f32_e32 v34, v33, v32
	v_fma_f32 v35, -v18, v34, v33
	v_fmac_f32_e32 v34, v35, v32
	v_fma_f32 v18, -v18, v34, v33
	v_div_fmas_f32 v18, v18, v32, v34
	v_div_fixup_f32 v16, v18, v16, 1.0
	v_cvt_pk_f16_f32 v17, v16, v17
	v_cvt_f32_f16_e32 v16, v17
	v_cvt_f32_f16_sdwa v17, v17 dst_sel:DWORD dst_unused:UNUSED_PAD src0_sel:WORD_1
	v_mov_b32_e32 v18, v19
	v_mov_b32_e32 v19, v20
	v_pk_fma_f32 v[68:69], v[18:19], v[16:17], v[68:69]
	v_pk_add_f32 v[16:17], v[94:95], 1.0 op_sel_hi:[1,0]
	s_nop 0
	v_div_scale_f32 v18, s[0:1], v17, v17, 1.0
	v_rcp_f32_e32 v19, v18
	s_nop 0
	v_fma_f32 v20, -v18, v19, 1.0
	v_fmac_f32_e32 v19, v20, v19
	v_div_scale_f32 v20, vcc, 1.0, v17, 1.0
	v_mul_f32_e32 v32, v20, v19
	v_fma_f32 v33, -v18, v32, v20
	v_fmac_f32_e32 v32, v33, v19
	v_fma_f32 v18, -v18, v32, v20
	v_div_fmas_f32 v18, v18, v19, v32
	v_div_fixup_f32 v17, v18, v17, 1.0
	v_div_scale_f32 v18, s[0:1], v16, v16, 1.0
	v_rcp_f32_e32 v19, v18
	s_nop 0
	v_fma_f32 v20, -v18, v19, 1.0
	v_fmac_f32_e32 v19, v20, v19
	v_div_scale_f32 v20, vcc, 1.0, v16, 1.0
	v_mul_f32_e32 v32, v20, v19
	v_fma_f32 v33, -v18, v32, v20
	v_fmac_f32_e32 v32, v33, v19
	v_fma_f32 v18, -v18, v32, v20
	v_div_fmas_f32 v18, v18, v19, v32
	v_div_fixup_f32 v16, v18, v16, 1.0
	v_cvt_pk_f16_f32 v17, v16, v17
	v_cvt_f32_f16_e32 v16, v17
	v_cvt_f32_f16_sdwa v17, v17 dst_sel:DWORD dst_unused:UNUSED_PAD src0_sel:WORD_1
	v_mov_b32_e32 v18, v21
	v_mov_b32_e32 v19, v22
	v_pk_fma_f32 v[66:67], v[18:19], v[16:17], v[66:67]
	v_pk_add_f32 v[16:17], v[92:93], 1.0 op_sel_hi:[1,0]
	s_nop 0
	v_div_scale_f32 v18, s[0:1], v17, v17, 1.0
	v_rcp_f32_e32 v19, v18
	s_nop 0
	v_fma_f32 v20, -v18, v19, 1.0
	v_fmac_f32_e32 v19, v20, v19
	v_div_scale_f32 v20, vcc, 1.0, v17, 1.0
	v_mul_f32_e32 v21, v20, v19
	v_fma_f32 v22, -v18, v21, v20
	v_fmac_f32_e32 v21, v22, v19
	v_fma_f32 v18, -v18, v21, v20
	v_div_fmas_f32 v18, v18, v19, v21
	v_div_fixup_f32 v17, v18, v17, 1.0
	v_div_scale_f32 v18, s[0:1], v16, v16, 1.0
	v_rcp_f32_e32 v19, v18
	s_nop 0
	v_fma_f32 v20, -v18, v19, 1.0
	v_fmac_f32_e32 v19, v20, v19
	v_div_scale_f32 v20, vcc, 1.0, v16, 1.0
	v_mul_f32_e32 v21, v20, v19
	v_fma_f32 v22, -v18, v21, v20
	v_fmac_f32_e32 v21, v22, v19
	v_fma_f32 v18, -v18, v21, v20
	v_div_fmas_f32 v18, v18, v19, v21
	v_div_fixup_f32 v16, v18, v16, 1.0
	v_cvt_pk_f16_f32 v17, v16, v17
	v_cvt_f32_f16_e32 v16, v17
; DI float sigmoid_f(float x) { return 1.f / (1.f + __expf(-x)); }
; template <int MB>
; DI void merge_tile(const Params& P, int layer, size_t row0, int nt, char* smem) {
;     ...
;         for (int v = 0; v < 16; ++v) gpk[mb][nb][v >> 3][v & 7] = (h16)sigmoid_f(pa2[mb][nb][v]);
;     zero_acc<MB>(pa2);
;     gemm_kloop<MB, true>(pa2, yn + row0 * LDY, LDY, wbrT + (size_t)(n * 1024 + nt * 256) * LDY, LDY, WB, smem);
; #pragma unroll
;     for (int mb = 0; mb < MB; ++mb)
; #pragma unroll
;       for (int nb = 0; nb < 2; ++nb)
; #pragma unroll
;         for (int v = 0; v < 16; ++v) macc[mb][nb][v] += (float)gpk[mb][nb][v >> 3][v & 7] * pa2[mb][nb][v];
	v_cvt_f32_f16_sdwa v17, v17 dst_sel:DWORD dst_unused:UNUSED_PAD src0_sel:WORD_1
	v_mov_b32_e32 v18, v23
	v_mov_b32_e32 v19, v24
	v_pk_fma_f32 v[64:65], v[18:19], v[16:17], v[64:65]
	v_pk_add_f32 v[16:17], v[90:91], 1.0 op_sel_hi:[1,0]
	s_nop 0
	v_div_scale_f32 v18, s[0:1], v17, v17, 1.0
	v_rcp_f32_e32 v19, v18
	s_nop 0
	v_fma_f32 v20, -v18, v19, 1.0
	v_fmac_f32_e32 v19, v20, v19
	v_div_scale_f32 v20, vcc, 1.0, v17, 1.0
	v_mul_f32_e32 v21, v20, v19
	v_fma_f32 v22, -v18, v21, v20
	v_fmac_f32_e32 v21, v22, v19
	v_fma_f32 v18, -v18, v21, v20
	v_div_fmas_f32 v18, v18, v19, v21
	v_div_fixup_f32 v17, v18, v17, 1.0
	v_div_scale_f32 v18, s[0:1], v16, v16, 1.0
	v_rcp_f32_e32 v19, v18
	s_nop 0
	v_fma_f32 v20, -v18, v19, 1.0
	v_fmac_f32_e32 v19, v20, v19
	v_div_scale_f32 v20, vcc, 1.0, v16, 1.0
	v_mul_f32_e32 v21, v20, v19
	v_fma_f32 v22, -v18, v21, v20
	v_fmac_f32_e32 v21, v22, v19
	v_fma_f32 v18, -v18, v21, v20
	v_div_fmas_f32 v18, v18, v19, v21
	v_div_fixup_f32 v16, v18, v16, 1.0
	v_cvt_pk_f16_f32 v17, v16, v17
	v_cvt_f32_f16_e32 v16, v17
	v_cvt_f32_f16_sdwa v17, v17 dst_sel:DWORD dst_unused:UNUSED_PAD src0_sel:WORD_1
	v_mov_b32_e32 v18, v25
	v_mov_b32_e32 v19, v26
	v_pk_fma_f32 v[62:63], v[18:19], v[16:17], v[62:63]
	v_pk_add_f32 v[16:17], v[88:89], 1.0 op_sel_hi:[1,0]
	s_nop 0
	v_div_scale_f32 v18, s[0:1], v17, v17, 1.0
	v_rcp_f32_e32 v19, v18
	s_nop 0
	v_fma_f32 v20, -v18, v19, 1.0
	v_fmac_f32_e32 v19, v20, v19
	v_div_scale_f32 v20, vcc, 1.0, v17, 1.0
	v_mul_f32_e32 v21, v20, v19
	v_fma_f32 v22, -v18, v21, v20
	v_fmac_f32_e32 v21, v22, v19
	v_fma_f32 v18, -v18, v21, v20
	v_div_fmas_f32 v18, v18, v19, v21
	v_div_fixup_f32 v17, v18, v17, 1.0
	v_div_scale_f32 v18, s[0:1], v16, v16, 1.0
	v_rcp_f32_e32 v19, v18
	s_nop 0
	v_fma_f32 v20, -v18, v19, 1.0
	v_fmac_f32_e32 v19, v20, v19
	v_div_scale_f32 v20, vcc, 1.0, v16, 1.0
	v_mul_f32_e32 v21, v20, v19
	v_fma_f32 v22, -v18, v21, v20
	v_fmac_f32_e32 v21, v22, v19
	v_fma_f32 v18, -v18, v21, v20
	v_div_fmas_f32 v18, v18, v19, v21
	v_div_fixup_f32 v16, v18, v16, 1.0
	v_cvt_pk_f16_f32 v17, v16, v17
	v_cvt_f32_f16_e32 v16, v17
	v_cvt_f32_f16_sdwa v17, v17 dst_sel:DWORD dst_unused:UNUSED_PAD src0_sel:WORD_1
	v_mov_b32_e32 v18, v27
	v_mov_b32_e32 v19, v28
	v_pk_fma_f32 v[60:61], v[18:19], v[16:17], v[60:61]
	v_pk_add_f32 v[16:17], v[86:87], 1.0 op_sel_hi:[1,0]
	s_nop 0
	v_div_scale_f32 v18, s[0:1], v17, v17, 1.0
	v_rcp_f32_e32 v19, v18
	s_nop 0
	v_fma_f32 v20, -v18, v19, 1.0
	v_fmac_f32_e32 v19, v20, v19
	v_div_scale_f32 v20, vcc, 1.0, v17, 1.0
	v_mul_f32_e32 v21, v20, v19
	v_fma_f32 v22, -v18, v21, v20
	v_fmac_f32_e32 v21, v22, v19
	v_fma_f32 v18, -v18, v21, v20
	v_div_fmas_f32 v18, v18, v19, v21
	v_div_fixup_f32 v17, v18, v17, 1.0
	v_div_scale_f32 v18, s[0:1], v16, v16, 1.0
	v_rcp_f32_e32 v19, v18
	s_nop 0
	v_fma_f32 v20, -v18, v19, 1.0
	v_fmac_f32_e32 v19, v20, v19
	v_div_scale_f32 v20, vcc, 1.0, v16, 1.0
	v_mul_f32_e32 v21, v20, v19
	v_fma_f32 v22, -v18, v21, v20
	v_fmac_f32_e32 v21, v22, v19
	v_fma_f32 v18, -v18, v21, v20
	v_div_fmas_f32 v18, v18, v19, v21
	v_div_fixup_f32 v16, v18, v16, 1.0
	v_cvt_pk_f16_f32 v17, v16, v17
	v_cvt_f32_f16_e32 v16, v17
	v_cvt_f32_f16_sdwa v17, v17 dst_sel:DWORD dst_unused:UNUSED_PAD src0_sel:WORD_1
	v_mov_b32_e32 v18, v29
	v_mov_b32_e32 v19, v30
	v_pk_fma_f32 v[58:59], v[18:19], v[16:17], v[58:59]
	v_pk_add_f32 v[16:17], v[84:85], 1.0 op_sel_hi:[1,0]
	s_nop 0
	v_div_scale_f32 v0, s[0:1], v17, v17, 1.0
	v_rcp_f32_e32 v18, v0
	s_nop 0
	v_fma_f32 v19, -v0, v18, 1.0
	v_fmac_f32_e32 v18, v19, v18
	v_div_scale_f32 v19, vcc, 1.0, v17, 1.0
	v_mul_f32_e32 v20, v19, v18
	v_fma_f32 v21, -v0, v20, v19
	v_fmac_f32_e32 v20, v21, v18
	v_fma_f32 v0, -v0, v20, v19
	v_div_fmas_f32 v0, v0, v18, v20
	v_div_fixup_f32 v0, v0, v17, 1.0
	v_div_scale_f32 v17, s[0:1], v16, v16, 1.0
	v_rcp_f32_e32 v18, v17
	s_nop 0
	v_fma_f32 v19, -v17, v18, 1.0
	v_fmac_f32_e32 v18, v19, v18
	v_div_scale_f32 v19, vcc, 1.0, v16, 1.0
	v_mul_f32_e32 v20, v19, v18
	v_fma_f32 v21, -v17, v20, v19
	v_fmac_f32_e32 v20, v21, v18
	v_fma_f32 v17, -v17, v20, v19
	v_div_fmas_f32 v17, v17, v18, v20
	v_div_fixup_f32 v16, v17, v16, 1.0
	v_cvt_pk_f16_f32 v0, v16, v0
	v_cvt_f32_f16_e32 v16, v0
	v_cvt_f32_f16_sdwa v17, v0 dst_sel:DWORD dst_unused:UNUSED_PAD src0_sel:WORD_1
	v_mov_b32_e32 v0, v1
	v_mov_b32_e32 v1, v2
	v_pk_fma_f32 v[56:57], v[0:1], v[16:17], v[56:57]
	v_pk_add_f32 v[0:1], v[82:83], 1.0 op_sel_hi:[1,0]
	s_nop 0
	v_div_scale_f32 v2, s[0:1], v1, v1, 1.0
	v_rcp_f32_e32 v16, v2
	s_nop 0
	v_fma_f32 v17, -v2, v16, 1.0
	v_fmac_f32_e32 v16, v17, v16
	v_div_scale_f32 v17, vcc, 1.0, v1, 1.0
	v_mul_f32_e32 v18, v17, v16
	v_fma_f32 v19, -v2, v18, v17
	v_fmac_f32_e32 v18, v19, v16
	v_fma_f32 v2, -v2, v18, v17
	v_div_fmas_f32 v2, v2, v16, v18
	v_div_fixup_f32 v1, v2, v1, 1.0
	v_div_scale_f32 v2, s[0:1], v0, v0, 1.0
	v_rcp_f32_e32 v16, v2
	s_nop 0
	v_fma_f32 v17, -v2, v16, 1.0
	v_fmac_f32_e32 v16, v17, v16
	v_div_scale_f32 v17, vcc, 1.0, v0, 1.0
	v_mul_f32_e32 v18, v17, v16
	v_fma_f32 v19, -v2, v18, v17
	v_fmac_f32_e32 v18, v19, v16
	v_fma_f32 v2, -v2, v18, v17
	v_div_fmas_f32 v2, v2, v16, v18
	v_div_fixup_f32 v0, v2, v0, 1.0
	v_cvt_pk_f16_f32 v1, v0, v1
; DI float sigmoid_f(float x) { return 1.f / (1.f + __expf(-x)); }
; template <int MB>
; DI void merge_tile(const Params& P, int layer, size_t row0, int nt, char* smem) {
;     ...
;         for (int v = 0; v < 16; ++v) gpk[mb][nb][v >> 3][v & 7] = (h16)sigmoid_f(pa2[mb][nb][v]);
;     zero_acc<MB>(pa2);
;     gemm_kloop<MB, true>(pa2, yn + row0 * LDY, LDY, wbrT + (size_t)(n * 1024 + nt * 256) * LDY, LDY, WB, smem);
; #pragma unroll
;     for (int mb = 0; mb < MB; ++mb)
; #pragma unroll
;       for (int nb = 0; nb < 2; ++nb)
; #pragma unroll
;         for (int v = 0; v < 16; ++v) macc[mb][nb][v] += (float)gpk[mb][nb][v >> 3][v & 7] * pa2[mb][nb][v];
;   }
	v_cvt_f32_f16_e32 v0, v1
	v_cvt_f32_f16_sdwa v1, v1 dst_sel:DWORD dst_unused:UNUSED_PAD src0_sel:WORD_1
	v_mov_b32_e32 v2, v3
	v_mov_b32_e32 v3, v4
	v_pk_fma_f32 v[54:55], v[2:3], v[0:1], v[54:55]
	v_pk_add_f32 v[0:1], v[80:81], 1.0 op_sel_hi:[1,0]
	s_nop 0
	v_div_scale_f32 v2, s[0:1], v1, v1, 1.0
	v_rcp_f32_e32 v3, v2
	s_nop 0
	v_fma_f32 v4, -v2, v3, 1.0
	v_fmac_f32_e32 v3, v4, v3
	v_div_scale_f32 v4, vcc, 1.0, v1, 1.0
	v_mul_f32_e32 v16, v4, v3
	v_fma_f32 v17, -v2, v16, v4
	v_fmac_f32_e32 v16, v17, v3
	v_fma_f32 v2, -v2, v16, v4
	v_div_fmas_f32 v2, v2, v3, v16
	v_div_fixup_f32 v1, v2, v1, 1.0
	v_div_scale_f32 v2, s[0:1], v0, v0, 1.0
	v_rcp_f32_e32 v3, v2
	s_nop 0
	v_fma_f32 v4, -v2, v3, 1.0
	v_fmac_f32_e32 v3, v4, v3
	v_div_scale_f32 v4, vcc, 1.0, v0, 1.0
	v_mul_f32_e32 v16, v4, v3
	v_fma_f32 v17, -v2, v16, v4
	v_fmac_f32_e32 v16, v17, v3
	v_fma_f32 v2, -v2, v16, v4
	v_div_fmas_f32 v2, v2, v3, v16
	v_div_fixup_f32 v0, v2, v0, 1.0
	v_cvt_pk_f16_f32 v1, v0, v1
	v_cvt_f32_f16_e32 v0, v1
	v_cvt_f32_f16_sdwa v1, v1 dst_sel:DWORD dst_unused:UNUSED_PAD src0_sel:WORD_1
	v_mov_b32_e32 v2, v5
	v_mov_b32_e32 v3, v6
	v_pk_fma_f32 v[52:53], v[2:3], v[0:1], v[52:53]
	v_pk_add_f32 v[0:1], v[78:79], 1.0 op_sel_hi:[1,0]
	s_nop 0
	v_div_scale_f32 v2, s[0:1], v1, v1, 1.0
	v_rcp_f32_e32 v3, v2
	s_nop 0
	v_fma_f32 v4, -v2, v3, 1.0
	v_fmac_f32_e32 v3, v4, v3
	v_div_scale_f32 v4, vcc, 1.0, v1, 1.0
	v_mul_f32_e32 v5, v4, v3
	v_fma_f32 v6, -v2, v5, v4
	v_fmac_f32_e32 v5, v6, v3
	v_fma_f32 v2, -v2, v5, v4
	v_div_fmas_f32 v2, v2, v3, v5
	v_div_fixup_f32 v1, v2, v1, 1.0
	v_div_scale_f32 v2, s[0:1], v0, v0, 1.0
	v_rcp_f32_e32 v3, v2
	s_nop 0
	v_fma_f32 v4, -v2, v3, 1.0
	v_fmac_f32_e32 v3, v4, v3
	v_div_scale_f32 v4, vcc, 1.0, v0, 1.0
	v_mul_f32_e32 v5, v4, v3
	v_fma_f32 v6, -v2, v5, v4
	v_fmac_f32_e32 v5, v6, v3
	v_fma_f32 v2, -v2, v5, v4
	v_div_fmas_f32 v2, v2, v3, v5
	v_div_fixup_f32 v0, v2, v0, 1.0
	v_cvt_pk_f16_f32 v1, v0, v1
	v_cvt_f32_f16_e32 v0, v1
	v_cvt_f32_f16_sdwa v1, v1 dst_sel:DWORD dst_unused:UNUSED_PAD src0_sel:WORD_1
	v_mov_b32_e32 v2, v7
	v_mov_b32_e32 v3, v8
	v_pk_fma_f32 v[50:51], v[2:3], v[0:1], v[50:51]
	v_pk_add_f32 v[0:1], v[76:77], 1.0 op_sel_hi:[1,0]
	s_nop 0
	v_div_scale_f32 v2, s[0:1], v1, v1, 1.0
	v_rcp_f32_e32 v3, v2
	s_nop 0
	v_fma_f32 v4, -v2, v3, 1.0
	v_fmac_f32_e32 v3, v4, v3
	v_div_scale_f32 v4, vcc, 1.0, v1, 1.0
	v_mul_f32_e32 v5, v4, v3
	v_fma_f32 v6, -v2, v5, v4
	v_fmac_f32_e32 v5, v6, v3
	v_fma_f32 v2, -v2, v5, v4
	v_div_fmas_f32 v2, v2, v3, v5
	v_div_fixup_f32 v1, v2, v1, 1.0
	v_div_scale_f32 v2, s[0:1], v0, v0, 1.0
	v_rcp_f32_e32 v3, v2
	s_nop 0
	v_fma_f32 v4, -v2, v3, 1.0
	v_fmac_f32_e32 v3, v4, v3
	v_div_scale_f32 v4, vcc, 1.0, v0, 1.0
	v_mul_f32_e32 v5, v4, v3
	v_fma_f32 v6, -v2, v5, v4
	v_fmac_f32_e32 v5, v6, v3
	v_fma_f32 v2, -v2, v5, v4
	v_div_fmas_f32 v2, v2, v3, v5
	v_div_fixup_f32 v0, v2, v0, 1.0
	v_cvt_pk_f16_f32 v1, v0, v1
	v_cvt_f32_f16_e32 v0, v1
	v_cvt_f32_f16_sdwa v1, v1 dst_sel:DWORD dst_unused:UNUSED_PAD src0_sel:WORD_1
	v_mov_b32_e32 v2, v9
	v_mov_b32_e32 v3, v10
	v_pk_fma_f32 v[48:49], v[2:3], v[0:1], v[48:49]
	v_pk_add_f32 v[0:1], v[74:75], 1.0 op_sel_hi:[1,0]
	s_nop 0
	v_div_scale_f32 v2, s[0:1], v1, v1, 1.0
	v_rcp_f32_e32 v3, v2
	s_nop 0
	v_fma_f32 v4, -v2, v3, 1.0
	v_fmac_f32_e32 v3, v4, v3
	v_div_scale_f32 v4, vcc, 1.0, v1, 1.0
	v_mul_f32_e32 v5, v4, v3
	v_fma_f32 v6, -v2, v5, v4
	v_fmac_f32_e32 v5, v6, v3
	v_fma_f32 v2, -v2, v5, v4
	v_div_fmas_f32 v2, v2, v3, v5
	v_div_fixup_f32 v1, v2, v1, 1.0
	v_div_scale_f32 v2, s[0:1], v0, v0, 1.0
	v_rcp_f32_e32 v3, v2
	s_nop 0
	v_fma_f32 v4, -v2, v3, 1.0
	v_fmac_f32_e32 v3, v4, v3
	v_div_scale_f32 v4, vcc, 1.0, v0, 1.0
	v_mul_f32_e32 v5, v4, v3
	v_fma_f32 v6, -v2, v5, v4
	v_fmac_f32_e32 v5, v6, v3
	v_fma_f32 v2, -v2, v5, v4
	v_div_fmas_f32 v2, v2, v3, v5
	v_div_fixup_f32 v0, v2, v0, 1.0
	v_cvt_pk_f16_f32 v1, v0, v1
	v_cvt_f32_f16_e32 v0, v1
	v_cvt_f32_f16_sdwa v1, v1 dst_sel:DWORD dst_unused:UNUSED_PAD src0_sel:WORD_1
	v_mov_b32_e32 v2, v11
	v_mov_b32_e32 v3, v12
	v_pk_fma_f32 v[46:47], v[2:3], v[0:1], v[46:47]
	v_pk_add_f32 v[0:1], v[72:73], 1.0 op_sel_hi:[1,0]
	s_nop 0
	v_div_scale_f32 v2, s[0:1], v1, v1, 1.0
	v_rcp_f32_e32 v3, v2
	s_nop 0
	v_fma_f32 v4, -v2, v3, 1.0
	v_fmac_f32_e32 v3, v4, v3
	v_div_scale_f32 v4, vcc, 1.0, v1, 1.0
	v_mul_f32_e32 v5, v4, v3
	v_fma_f32 v6, -v2, v5, v4
	v_fmac_f32_e32 v5, v6, v3
	v_fma_f32 v2, -v2, v5, v4
	v_div_fmas_f32 v2, v2, v3, v5
	v_div_fixup_f32 v1, v2, v1, 1.0
	v_div_scale_f32 v2, s[0:1], v0, v0, 1.0
	v_rcp_f32_e32 v3, v2
	s_nop 0
	v_fma_f32 v4, -v2, v3, 1.0
	v_fmac_f32_e32 v3, v4, v3
	v_div_scale_f32 v4, vcc, 1.0, v0, 1.0
	v_mul_f32_e32 v5, v4, v3
	v_fma_f32 v6, -v2, v5, v4
	v_fmac_f32_e32 v5, v6, v3
	v_fma_f32 v2, -v2, v5, v4
	v_div_fmas_f32 v2, v2, v3, v5
	v_div_fixup_f32 v0, v2, v0, 1.0
	v_cvt_pk_f16_f32 v1, v0, v1
	v_cvt_f32_f16_e32 v0, v1
	v_cvt_f32_f16_sdwa v1, v1 dst_sel:DWORD dst_unused:UNUSED_PAD src0_sel:WORD_1
	v_mov_b32_e32 v2, v13
	v_mov_b32_e32 v3, v14
	v_pk_fma_f32 v[44:45], v[2:3], v[0:1], v[44:45]
	s_cbranch_scc1 .LBB0_58
	s_mov_b64 s[44:45], 0xb28180
	s_mov_b64 vcc, 0x32e6180
	s_branch .LBB0_62

; DI size_t wbase(int layer) { return (layer & 1) ? WS_W1 : WS_WINT; }
; DI void wait_vm0() { asm volatile("s_waitcnt vmcnt(0)" ::: "memory"); }
; DI int otid() { int t = threadIdx.x; asm volatile("" : "+v"(t)); return t; }
; template <int MB, bool SWAP>
; DI void gemm_kloop(f32x16 (&acc)[MB][2], const h16* __restrict__ A, int lda, const h16* __restrict__ B, int ldb, int K, char* lds) {
;     ...
;   const int tid = otid(), w = tid >> 6, lane = tid & 63;
;   const int wr = w >> 2, wc = w & 3;
;   const int lrow = w * 8 + (lane >> 3), pch = lane & 7;
;   const int gch = pch ^ ((lrow >> 1) & 7);
;   const unsigned voa = (unsigned)(lrow * lda + gch * 8) * 2u, vob = (unsigned)(lrow * ldb + gch * 8) * 2u;
;   const int lofs = lrow * 128 + pch * 16;
;   const int r32 = lane & 31, hh = lane >> 5, sw = (r32 >> 1) & 7;
;   const int a_rd = (wr * 32 * MB + r32) * 128;
;   const int b_rd = A_BYTES + (wc * 64 + r32) * 128;
;   const int nk = K >> 6;
;   constexpr int NP = MB + 4;
;   auto piece = [&](int p, int kt, int buf) {
;     char* s = lds + buf * STAGE;
;     if (p < MB) __builtin_amdgcn_global_load_lds((const unsigned*)((const char*)(A + (size_t)p * 64 * lda + kt * 64) + voa), (unsigned*)(s + p * 8192 + lofs), 16, 0, 0);
;     else __builtin_amdgcn_global_load_lds((const unsigned*)((const char*)(B + (size_t)(p - MB) * 64 * ldb + kt * 64) + vob), (unsigned*)(s + A_BYTES + (p - MB) * 8192 + lofs), 16, 0, 0);
;   };
;   wait_vm0();
; #pragma unroll
;   for (int p = 0; p < NP; ++p) piece(p, 0, 0);
; #pragma unroll
;   for (int p = 0; p < NP; ++p) piece(p, 1, 1);
; template <int MB>
; DI void out_tile(const Params& P, int layer, int row0, int nt, char* smem) {
;   const h16* mg = (const h16*)(P.ws + WS_R1);
;   const h16* woutT = (const h16*)(P.ws + wbase(layer) + OFF_WOUTT);
;   const float* mods = (const float*)(P.ws + WS_MODS) + (size_t)layer * 17 * 3072;
;   float* ctxw = (float*)(P.ws + WS_CTXW);
;   f32x16 acc[MB][2];
;   zero_acc<MB>(acc);
;   gemm_kloop<MB, true>(acc, mg + (size_t)row0 * LDH, LDH, woutT + (size_t)(nt * 256) * LDH, LDH, D, smem);
.LBB0_721:
	s_add_i32 s2, s39, s81
	s_cmp_ge_i32 s2, s70
	s_cbranch_scc1 .LBB0_720
	v_mov_b32_e32 v6, v208
	s_bfe_u32 s24, s38, 0x20003
	v_ashrrev_i32_e32 v7, 3, v6
	v_bfe_u32 v8, v6, 3, 3
	v_and_or_b32 v0, v7, -8, v8
	v_lshrrev_b32_e32 v1, 1, v0
	v_xor_b32_e32 v1, v1, v6
	v_lshlrev_b32_e32 v1, 3, v1
	v_mul_lo_u32 v2, v0, s6
	v_and_b32_e32 v9, 56, v1
	v_or_b32_e32 v1, v9, v2
	s_ashr_i32 s52, s2, 2
	v_lshlrev_b32_e32 v128, 1, v1
	v_lshlrev_b32_e32 v1, 4, v6
	s_mul_i32 s33, s24, 0x88000
	s_and_b32 s24, s52, 0x1fffff8
	s_and_b32 s25, s2, 7
	v_and_b32_e32 v1, 0x70, v1
	s_and_b32 s3, s97, 7
	s_or_b32 s24, s24, s25
	v_lshl_or_b32 v10, v0, 7, v1
	s_lshl_b32 s3, s3, 7
	s_bfe_u32 s75, s2, 0x20003
	s_lshl_b32 s2, s24, 7
	s_mul_i32 s24, s24, 0x44000
	v_add_u32_e32 v74, 0, v10
	s_mul_hi_i32 s25, s2, 0x880
	s_add_u32 s24, s48, s24
	v_readfirstlane_b32 s53, v74
	s_addc_u32 s25, s49, s25
	s_nop 0
	s_mov_b32 m0, s53
	v_add_u32_e32 v13, 0x2000, v74
	v_lshl_add_u64 v[2:3], s[24:25], 0, v[128:129]
	global_load_lds_dwordx4 v128, s[24:25]
	s_mov_b64 s[54:55], 0x22000
	v_readfirstlane_b32 s24, v13
	s_mul_i32 s50, s75, 0x88000
	v_lshl_add_u64 v[4:5], v[2:3], 0, s[54:55]
	s_mov_b32 m0, s24
	s_add_u32 s50, s87, s50
	v_and_b32_e32 v0, 31, v6
	v_lshrrev_b32_e32 v1, 2, v6
	global_load_lds_dwordx4 v[4:5], off
	v_add_u32_e32 v4, 0x4000, v74
	s_addc_u32 s51, s96, 0
	v_and_or_b32 v12, v1, s7, v0
	v_lshlrev_b32_e32 v0, 7, v6
	v_readfirstlane_b32 s24, v4
	v_add_u32_e32 v13, 0x6000, v74
	v_and_b32_e32 v68, 0x6f80, v0
	v_lshl_add_u64 v[0:1], s[50:51], 0, v[128:129]
	s_mov_b32 m0, s24
	v_readfirstlane_b32 s24, v13
	global_load_lds_dwordx4 v128, s[50:51]
	v_lshl_add_u64 v[4:5], v[0:1], 0, s[54:55]
	s_mov_b32 m0, s24
	s_mov_b64 s[24:25], 0x44000
	v_add_u32_e32 v13, 0x8000, v74
	global_load_lds_dwordx4 v[4:5], off
	v_lshl_add_u64 v[4:5], v[0:1], 0, s[24:25]
	v_readfirstlane_b32 s24, v13
	s_mov_b32 m0, s24
	s_mov_b64 s[24:25], 0x66000
	v_add_u32_e32 v13, 0xa000, v74
	global_load_lds_dwordx4 v[4:5], off
	v_lshl_add_u64 v[4:5], v[0:1], 0, s[24:25]
	v_readfirstlane_b32 s24, v13
	v_lshlrev_b32_e32 v70, 7, v12
	v_add_u32_e32 v12, 0xc000, v74
	s_mov_b32 m0, s24
	v_readfirstlane_b32 s24, v12
	global_load_lds_dwordx4 v[4:5], off
	v_lshl_add_u64 v[4:5], v[2:3], 0, s[22:23]
	s_mov_b32 m0, s24
	s_mov_b64 s[50:51], 0x22080
	global_load_lds_dwordx4 v[4:5], off
	v_add_u32_e32 v4, 0xe000, v74
	v_lshl_add_u64 v[2:3], v[2:3], 0, s[50:51]
	v_readfirstlane_b32 s24, v4
	v_add_u32_e32 v4, s8, v10
	s_mov_b32 m0, s24
	v_readfirstlane_b32 s24, v4
	v_add_u32_e32 v4, s9, v10
	global_load_lds_dwordx4 v[2:3], off
	v_lshl_add_u64 v[2:3], v[0:1], 0, s[22:23]
	s_mov_b32 m0, s24
	v_readfirstlane_b32 s24, v4
	global_load_lds_dwordx4 v[2:3], off
	v_lshl_add_u64 v[2:3], v[0:1], 0, s[50:51]
	s_mov_b32 m0, s24
	s_mov_b64 s[24:25], 0x44080
	v_add_u32_e32 v4, s79, v10
	global_load_lds_dwordx4 v[2:3], off
	v_lshl_add_u64 v[2:3], v[0:1], 0, s[24:25]
	v_readfirstlane_b32 s24, v4
	s_mov_b32 m0, s24
	s_mov_b64 s[24:25], 0x66080
	global_load_lds_dwordx4 v[2:3], off
	v_add_u32_e32 v2, s10, v10
	v_lshl_add_u64 v[0:1], v[0:1], 0, s[24:25]
	v_readfirstlane_b32 s24, v2
	s_mov_b32 m0, s24
	v_lshrrev_b32_e32 v11, 1, v6
	global_load_lds_dwordx4 v[0:1], off
	v_bfe_u32 v13, v6, 5, 1
	v_bfe_u32 v0, v6, 1, 3
	v_bitop3_b32 v1, v13, v11, 7 bitop3:0x78
	v_lshlrev_b32_e32 v73, 4, v1
	v_bitop3_b32 v1, v13, v0, 2 bitop3:0x36
	v_lshlrev_b32_e32 v72, 4, v1
	v_bitop3_b32 v1, v13, v0, 4 bitop3:0x36
	v_bitop3_b32 v0, v13, v0, 6 bitop3:0x36
	s_lshl_b32 s24, s52, 7
	v_lshlrev_b32_e32 v69, 4, v0
	s_and_b32 s24, s24, 0xfffffc00
	v_lshrrev_b32_e32 v0, 3, v7
	s_or_b32 s3, s24, s3
	v_mul_lo_u32 v0, v0, s11
	v_readlane_b32 s52, v253, 1
	s_mul_hi_i32 s25, s3, 0x880
	s_mulk_i32 s3, 0x880
	v_mad_u32_u24 v0, v8, s6, v0
	v_readlane_b32 s66, v253, 15
	v_or_b32_e32 v0, v0, v9
	v_readlane_b32 s67, v253, 16
	s_add_u32 s24, s66, s3
	v_lshlrev_b32_e32 v128, 1, v0
	s_addc_u32 s25, s67, s25
	v_lshl_add_u64 v[64:65], s[24:25], 0, v[128:129]
	s_add_u32 s24, s84, s33
	v_readlane_b32 s53, v253, 2
	v_readlane_b32 s54, v253, 3
	v_readlane_b32 s55, v253, 4
	v_readlane_b32 s56, v253, 5
	v_readlane_b32 s57, v253, 6
	v_readlane_b32 s58, v253, 7
	v_readlane_b32 s59, v253, 8
	v_readlane_b32 s60, v253, 9
	v_readlane_b32 s61, v253, 10
	v_readlane_b32 s62, v253, 11
	v_readlane_b32 s63, v253, 12
	s_addc_u32 s25, s86, 0
	v_mov_b32_e32 v0, 0
	v_lshlrev_b32_e32 v71, 4, v1
	v_lshl_add_u64 v[66:67], s[24:25], 0, v[128:129]
	s_mov_b32 s3, 0
	s_mov_b64 s[50:51], 0
	v_mov_b32_e32 v1, v0
	v_mov_b32_e32 v2, v0
	v_mov_b32_e32 v3, v0
	v_mov_b32_e32 v4, v0
	v_mov_b32_e32 v5, v0
	v_mov_b32_e32 v6, v0
	v_mov_b32_e32 v7, v0
	v_mov_b32_e32 v8, v0
	v_mov_b32_e32 v9, v0
	v_mov_b32_e32 v10, v0
	v_mov_b32_e32 v11, v0
	v_mov_b32_e32 v12, v0
	v_mov_b32_e32 v13, v0
	v_mov_b32_e32 v14, v0
	v_mov_b32_e32 v15, v0
	v_mov_b32_e32 v16, v0
	v_mov_b32_e32 v17, v0
	v_mov_b32_e32 v18, v0
	v_mov_b32_e32 v19, v0
	v_mov_b32_e32 v20, v0
	v_mov_b32_e32 v21, v0
	v_mov_b32_e32 v22, v0
	v_mov_b32_e32 v23, v0
	v_mov_b32_e32 v24, v0
	v_mov_b32_e32 v25, v0
	v_mov_b32_e32 v26, v0
	v_mov_b32_e32 v27, v0
	v_mov_b32_e32 v28, v0
	v_mov_b32_e32 v29, v0
	v_mov_b32_e32 v30, v0
	v_mov_b32_e32 v31, v0
	v_mov_b32_e32 v32, v0
	v_mov_b32_e32 v33, v0
	v_mov_b32_e32 v34, v0
	v_mov_b32_e32 v35, v0
	v_mov_b32_e32 v36, v0
	v_mov_b32_e32 v37, v0
	v_mov_b32_e32 v38, v0
	v_mov_b32_e32 v39, v0
	v_mov_b32_e32 v40, v0
	v_mov_b32_e32 v41, v0
	v_mov_b32_e32 v42, v0
	v_mov_b32_e32 v43, v0
	v_mov_b32_e32 v44, v0
	v_mov_b32_e32 v45, v0
	v_mov_b32_e32 v46, v0
	v_mov_b32_e32 v47, v0
	v_mov_b32_e32 v48, v0
	v_mov_b32_e32 v49, v0
	v_mov_b32_e32 v50, v0
	v_mov_b32_e32 v51, v0
	v_mov_b32_e32 v52, v0
	v_mov_b32_e32 v53, v0
	v_mov_b32_e32 v54, v0
	v_mov_b32_e32 v55, v0
	v_mov_b32_e32 v56, v0
	v_mov_b32_e32 v57, v0
	v_mov_b32_e32 v58, v0
	v_mov_b32_e32 v59, v0
	v_mov_b32_e32 v60, v0
	v_mov_b32_e32 v61, v0
	v_mov_b32_e32 v62, v0
	v_mov_b32_e32 v63, v0
	s_mov_b64 s[52:53], 0x14e8100
	s_mov_b64 s[54:55], 0x7f88100
	s_mov_b64 s[56:57], 0x7f66100
	s_mov_b64 s[58:59], 0x150a100
	s_mov_b64 s[60:61], 0x154e100
	s_mov_b64 s[62:63], 0x152c100
	v_readlane_b32 s64, v253, 13
	v_readlane_b32 s65, v253, 14
	v_readfirstlane_b32 s25, v208
	s_nop 0
	s_lshr_b32 s25, s25, 8
	s_cmp_lg_u32 s25, 0
	s_cbranch_scc1 .Lstg723_top

; DI void wait_vm0() { asm volatile("s_waitcnt vmcnt(0)" ::: "memory"); }
; DI int otid() { int t = threadIdx.x; asm volatile("" : "+v"(t)); return t; }
;   DI int item(int i) const { const int li = j + i * nxb; if (li >= per) return -1; const int lin = xcd * per + li; return lin < total ? lin : -1; }
; template <int MB, bool SWAP>
; DI void gemm_kloop(f32x16 (&acc)[MB][2], const h16* __restrict__ A, int lda, const h16* __restrict__ B, int ldb, int K, char* lds) {
;     ...
;   const int tid = otid(), w = tid >> 6, lane = tid & 63;
;   const int wr = w >> 2, wc = w & 3;
;   const int lrow = w * 8 + (lane >> 3), pch = lane & 7;
;   const int gch = pch ^ ((lrow >> 1) & 7);
;   const unsigned voa = (unsigned)(lrow * lda + gch * 8) * 2u, vob = (unsigned)(lrow * ldb + gch * 8) * 2u;
;   const int lofs = lrow * 128 + pch * 16;
;   const int r32 = lane & 31, hh = lane >> 5, sw = (r32 >> 1) & 7;
;   const int a_rd = (wr * 32 * MB + r32) * 128;
;   const int b_rd = A_BYTES + (wc * 64 + r32) * 128;
;   const int nk = K >> 6;
;   constexpr int NP = MB + 4;
;   auto piece = [&](int p, int kt, int buf) {
;     char* s = lds + buf * STAGE;
;     if (p < MB) __builtin_amdgcn_global_load_lds((const unsigned*)((const char*)(A + (size_t)p * 64 * lda + kt * 64) + voa), (unsigned*)(s + p * 8192 + lofs), 16, 0, 0);
;     else __builtin_amdgcn_global_load_lds((const unsigned*)((const char*)(B + (size_t)(p - MB) * 64 * ldb + kt * 64) + vob), (unsigned*)(s + A_BYTES + (p - MB) * 8192 + lofs), 16, 0, 0);
;   };
;   wait_vm0();
; #pragma unroll
;   for (int p = 0; p < NP; ++p) piece(p, 0, 0);
; #pragma unroll
;   for (int p = 0; p < NP; ++p) piece(p, 1, 1);
; DI void phase_out(const Params& P, int layer, char* smem) {
;     ...
;   for_items_xcd(nhalf, [&](int h) {
;     const int item = nfull + (h >> 1);
;     const int mt = (item >> 5) * 8 + (item & 7), nt = (item & 31) >> 3;
;     out_tile<1>(P, layer, mt * 128 + (h & 1) * 64, nt, smem);
;   });
.LBB0_748:
	s_add_i32 s2, s77, s86
	s_cmp_ge_i32 s2, s78
	s_cbranch_scc1 .LBB0_747
	v_mov_b32_e32 v6, v208
	s_ashr_i32 s3, s2, 1
	v_ashrrev_i32_e32 v7, 3, v6
	v_bfe_u32 v8, v6, 3, 3
	v_and_or_b32 v0, v7, -8, v8
	v_lshrrev_b32_e32 v1, 1, v0
	s_add_i32 s24, s3, s70
	v_xor_b32_e32 v1, v1, v6
	s_ashr_i32 s53, s24, 2
	v_lshlrev_b32_e32 v1, 3, v1
	s_and_b32 s25, s53, 0x1fffff8
	s_and_b32 s54, s3, 7
	v_mul_lo_u32 v2, v0, s6
	v_and_b32_e32 v9, 56, v1
	s_or_b32 s3, s25, s54
	s_lshl_b32 s2, s2, 6
	v_or_b32_e32 v1, v9, v2
	s_lshl_b32 s3, s3, 7
	s_and_b32 s2, s2, 64
	v_lshlrev_b32_e32 v128, 1, v1
	v_lshlrev_b32_e32 v1, 4, v6
	s_or_b32 s33, s3, s2
	v_and_b32_e32 v1, 0x70, v1
	s_and_b32 s52, s74, 64
	s_bfe_u32 s80, s24, 0x20003
	s_mul_i32 s2, s33, 0x880
	v_lshl_or_b32 v10, v0, 7, v1
	s_mul_hi_i32 s3, s33, 0x880
	s_add_u32 s2, s48, s2
	v_add_u32_e32 v42, 0, v10
	s_addc_u32 s3, s49, s3
	s_mul_i32 s55, s80, 0x88000
	v_readfirstlane_b32 s56, v42
	s_add_u32 s24, s75, s55
	s_nop 0
	s_mov_b32 m0, s56
	v_add_u32_e32 v4, 0x2000, v42
	s_addc_u32 s25, s76, 0
	v_lshl_add_u64 v[2:3], s[2:3], 0, v[128:129]
	global_load_lds_dwordx4 v128, s[2:3]
	v_readfirstlane_b32 s2, v4
	v_lshl_add_u64 v[0:1], s[24:25], 0, v[128:129]
	s_mov_b32 m0, s2
	s_mov_b64 s[2:3], 0x22000
	v_add_u32_e32 v11, 0x4000, v42
	v_lshl_add_u64 v[4:5], v[0:1], 0, s[2:3]
	v_readfirstlane_b32 s2, v11
	global_load_lds_dwordx4 v128, s[24:25]
	s_mov_b32 m0, s2
	s_mov_b64 s[2:3], 0x44000
	v_add_u32_e32 v11, 0x6000, v42
	global_load_lds_dwordx4 v[4:5], off
	v_lshl_add_u64 v[4:5], v[0:1], 0, s[2:3]
	v_readfirstlane_b32 s2, v11
	s_mov_b32 m0, s2
	s_mov_b64 s[2:3], 0x66000
	v_add_u32_e32 v11, 0x8000, v42
	global_load_lds_dwordx4 v[4:5], off
	v_lshl_add_u64 v[4:5], v[0:1], 0, s[2:3]
	v_readfirstlane_b32 s2, v11
	s_mov_b32 m0, s2
	v_lshl_add_u64 v[2:3], v[2:3], 0, s[22:23]
	global_load_lds_dwordx4 v[4:5], off
	v_add_u32_e32 v4, 0xa000, v42
	v_readlane_b32 s36, v253, 1
	v_readfirstlane_b32 s2, v4
	v_add_u32_e32 v4, 0xc000, v42
	s_mov_b32 m0, s2
	v_readfirstlane_b32 s2, v4
	global_load_lds_dwordx4 v[2:3], off
	v_lshl_add_u64 v[2:3], v[0:1], 0, s[22:23]
	s_mov_b32 m0, s2
	s_mov_b64 s[2:3], 0x22080
	v_add_u32_e32 v4, 0xe000, v42
	global_load_lds_dwordx4 v[2:3], off
	v_lshl_add_u64 v[2:3], v[0:1], 0, s[2:3]
	v_readfirstlane_b32 s2, v4
	s_mov_b32 m0, s2
	s_mov_b64 s[2:3], 0x44080
	v_add_u32_e32 v4, s8, v10
	global_load_lds_dwordx4 v[2:3], off
	v_lshl_add_u64 v[2:3], v[0:1], 0, s[2:3]
	v_readfirstlane_b32 s2, v4
	s_mov_b32 m0, s2
	s_mov_b64 s[2:3], 0x66080
	global_load_lds_dwordx4 v[2:3], off
	v_add_u32_e32 v2, s9, v10
	v_lshl_add_u64 v[0:1], v[0:1], 0, s[2:3]
	v_readfirstlane_b32 s2, v2
	s_mov_b32 m0, s2
	v_lshlrev_b32_e32 v2, 7, v6
	global_load_lds_dwordx4 v[0:1], off
	v_and_b32_e32 v0, 31, v6
	v_lshrrev_b32_e32 v1, 1, v6
	v_and_or_b32 v0, v7, s16, v0
	v_and_b32_e32 v39, 0x6f80, v2
	v_bfe_u32 v2, v6, 5, 1
	v_lshlrev_b32_e32 v41, 7, v0
	v_bfe_u32 v0, v6, 1, 3
	v_bitop3_b32 v1, v2, v1, 7 bitop3:0x78
	v_lshlrev_b32_e32 v40, 4, v1
	v_bitop3_b32 v1, v2, v0, 2 bitop3:0x36
	s_lshl_b32 s2, s53, 7
	v_lshlrev_b32_e32 v38, 4, v1
	v_bitop3_b32 v1, v2, v0, 4 bitop3:0x36
	v_bitop3_b32 v0, v2, v0, 6 bitop3:0x36
	s_and_b32 s2, s2, 0xfffffc00
	s_lshl_b32 s3, s54, 7
	v_lshlrev_b32_e32 v36, 4, v0
	s_or_b32 s2, s2, s3
	v_lshrrev_b32_e32 v0, 3, v7
	s_or_b32 s2, s2, s52
	v_mul_lo_u32 v0, v0, s11
	s_mul_hi_i32 s3, s2, 0x880
	s_mulk_i32 s2, 0x880
	v_mad_u32_u24 v0, v8, s6, v0
	v_readlane_b32 s50, v253, 15
	v_or_b32_e32 v0, v0, v9
	v_readlane_b32 s51, v253, 16
	s_add_u32 s2, s50, s2
	v_lshlrev_b32_e32 v128, 1, v0
	s_addc_u32 s3, s51, s3
	v_lshl_add_u64 v[32:33], s[2:3], 0, v[128:129]
	s_add_u32 s2, s57, s55
	v_readlane_b32 s37, v253, 2
	v_readlane_b32 s38, v253, 3
	v_readlane_b32 s39, v253, 4
	s_addc_u32 s3, s62, 0
	v_mov_b32_e32 v16, 0
	v_lshlrev_b32_e32 v37, 4, v1
	v_lshl_add_u64 v[34:35], s[2:3], 0, v[128:129]
	s_mov_b32 s24, 0
	s_mov_b64 s[2:3], 0
	v_mov_b32_e32 v17, v16
	v_mov_b32_e32 v18, v16
	v_mov_b32_e32 v19, v16
	v_mov_b32_e32 v20, v16
	v_mov_b32_e32 v21, v16
	v_mov_b32_e32 v22, v16
	v_mov_b32_e32 v23, v16
	v_mov_b32_e32 v24, v16
	v_mov_b32_e32 v25, v16
	v_mov_b32_e32 v26, v16
	v_mov_b32_e32 v27, v16
	v_mov_b32_e32 v28, v16
	v_mov_b32_e32 v29, v16
	v_mov_b32_e32 v30, v16
	v_mov_b32_e32 v31, v16
	v_mov_b32_e32 v0, v16
	v_mov_b32_e32 v1, v16
	v_mov_b32_e32 v2, v16
	v_mov_b32_e32 v3, v16
	v_mov_b32_e32 v4, v16
	v_mov_b32_e32 v5, v16
	v_mov_b32_e32 v6, v16
	v_mov_b32_e32 v7, v16
	v_mov_b32_e32 v8, v16
	v_mov_b32_e32 v9, v16
	v_mov_b32_e32 v10, v16
	v_mov_b32_e32 v11, v16
	v_mov_b32_e32 v12, v16
	v_mov_b32_e32 v13, v16
	v_mov_b32_e32 v14, v16
	v_mov_b32_e32 v15, v16
	s_mov_b64 s[36:37], 0x152c100
	s_mov_b64 s[38:39], 0x154e180
	v_readlane_b32 s40, v253, 5
	v_readlane_b32 s41, v253, 6
	v_readlane_b32 s42, v253, 7
	v_readlane_b32 s43, v253, 8
	v_readlane_b32 s44, v253, 9
	v_readlane_b32 s45, v253, 10
	v_readlane_b32 s46, v253, 11
	v_readlane_b32 s47, v253, 12
	v_readlane_b32 s48, v253, 13
	v_readlane_b32 s49, v253, 14
